# memory cross-attention (phase 7): output tile leaves through a wave-private swizzled LDS image as 512-byte row pieces (8 dwordx4 stores per wave instead of 16 dwordx2)
# speedup vs baseline: 1.2235x; 1.0075x over previous
; DEVI int launder(int x) { asm volatile("" : "+v"(x)); return x; }
; #define LOADK_(kbx) LK1_(0, kbx) LK1_(1, kbx) LK1_(2, kbx) LK1_(3, kbx) LK1_(4, kbx) LK1_(5, kbx) LK1_(6, kbx) LK1_(7, kbx)
; #define STOREK_() SK1_(0) SK1_(1) SK1_(2) SK1_(3) SK1_(4) SK1_(5) SK1_(6) SK1_(7)
; #define LOADV_(kbx) LV1_(0, kbx) LV1_(1, kbx) LV1_(2, kbx) LV1_(3, kbx) LV1_(4, kbx) LV1_(5, kbx) LV1_(6, kbx) LV1_(7, kbx)
; #define STOREV_() SV1_(0) SV1_(1) SV1_(2) SV1_(3) SV1_(4) SV1_(5) SV1_(6) SV1_(7)
; DEVI void phase_memattn(const Params& p, unsigned char* smem) {
;     ...
;   for (int tile = blockIdx.x; tile < 2048; tile += gridDim.x) {
;     const int tid = launder(threadIdx.x), lane = tid & 63, w = tid >> 6, col = lane & 15, quad = lane >> 4;
;     const int b = tile >> 7, head = (tile >> 5) & 3, q0 = (tile & 31) * 64;
;     const size_t tok = (size_t)b * T + q0 + 16 * w + col;
;     bf16x8 qf[1][8];
; #pragma unroll
;     for (int ks = 0; ks < 8; ++ks) qf[0][ks] = *(const bf16x8*)(p.qm + tok * LDA + head * 256 + 32 * ks + 8 * quad);
;     float m[1] = {-1e30f}, l[1] = {0.f};
;     f32x4 o[1][16];
; #pragma unroll
;     for (int dt = 0; dt < 16; ++dt) o[0][dt] = f32x4{0.f, 0.f, 0.f, 0.f};
;     uint4 rg0, rg1, rg2, rg3, rg4, rg5, rg6, rg7;
;     const int krow = tid >> 5, kch = (tid & 31) << 3;
;     const int vrow = tid >> 3, vch = (tid & 7) << 3;
;     ...
;     __syncthreads();
;     LOADK_(0)
;     STOREK_()
;     LOADV_(0)
;     __syncthreads();
; #pragma unroll 1
;     for (int kb = 0; kb < 4; ++kb) {
;       bf16x8 pb[1][2];
;       attn_qk<256, 1, 264>(sK, qf, o, m, l, c2, lane, [&](int, int) { return true; }, pb);
;       STOREV_()
;       if (kb < 3) { LOADK_(kb + 1) }
;       __syncthreads();
.Lp7_tile:
	s_lshr_b32 s10, s8, 7
	s_bfe_u32 s11, s8, 0x20005
	s_and_b32 s12, s8, 31
	s_lshl_b32 s12, s12, 6
	s_lshl_b32 s14, s11, 9
	s_lshl_b32 s13, s10, 11
	s_add_u32 s13, s13, s12
	s_mul_i32 s13, s13, 0x880
	s_add_u32 s13, s13, s14
	v_add_u32_e32 v231, s13, v220
	global_load_dwordx4 v[0:3], v231, s[0:1]
	global_load_dwordx4 v[4:7], v231, s[0:1] offset:64
	global_load_dwordx4 v[8:11], v231, s[0:1] offset:128
	global_load_dwordx4 v[12:15], v231, s[0:1] offset:192
	global_load_dwordx4 v[16:19], v231, s[0:1] offset:256
	global_load_dwordx4 v[20:23], v231, s[0:1] offset:320
	global_load_dwordx4 v[24:27], v231, s[0:1] offset:384
	global_load_dwordx4 v[28:31], v231, s[0:1] offset:448
	s_mul_i32 s16, s10, 0x88000
	s_add_u32 s16, s16, s14
	v_add_u32_e32 v231, s16, v221
	global_load_dwordx4 v[144:147], v231, s[2:3]
	s_add_u32 s16, s16, 0x4400
	v_add_u32_e32 v232, s16, v221
	global_load_dwordx4 v[148:151], v232, s[2:3]
	s_add_u32 s16, s16, 0x4400
	v_add_u32_e32 v233, s16, v221
	global_load_dwordx4 v[152:155], v233, s[2:3]
	s_add_u32 s16, s16, 0x4400
	v_add_u32_e32 v234, s16, v221
	global_load_dwordx4 v[156:159], v234, s[2:3]
	s_add_u32 s16, s16, 0x4400
	v_add_u32_e32 v231, s16, v221
	global_load_dwordx4 v[160:163], v231, s[2:3]
	s_add_u32 s16, s16, 0x4400
	v_add_u32_e32 v232, s16, v221
	global_load_dwordx4 v[164:167], v232, s[2:3]
	s_add_u32 s16, s16, 0x4400
	v_add_u32_e32 v233, s16, v221
	global_load_dwordx4 v[168:171], v233, s[2:3]
	s_add_u32 s16, s16, 0x4400
	v_add_u32_e32 v234, s16, v221
	global_load_dwordx4 v[172:175], v234, s[2:3]
	v_mov_b32_e32 v229, 0xf149f2ca
	v_mov_b32_e32 v230, 0
	s_waitcnt vmcnt(0)
	ds_write_b128 v223, v[144:147]
	ds_write_b128 v223, v[148:151] offset:4224
	ds_write_b128 v223, v[152:155] offset:8448
	ds_write_b128 v223, v[156:159] offset:12672
	ds_write_b128 v223, v[160:163] offset:16896
	ds_write_b128 v223, v[164:167] offset:21120
	ds_write_b128 v223, v[168:171] offset:25344
	ds_write_b128 v223, v[172:175] offset:29568
	s_lshl_b32 s16, s10, 2
	s_add_u32 s16, s16, s11
	s_lshl_b32 s16, s16, 17
	v_add_u32_e32 v231, s16, v222
	global_load_dwordx4 v[176:179], v231, s[4:5]
	s_add_u32 s16, s16, 0x4000
	v_add_u32_e32 v232, s16, v222
	global_load_dwordx4 v[180:183], v232, s[4:5]
	s_add_u32 s16, s16, 0x4000
	v_add_u32_e32 v233, s16, v222
	global_load_dwordx4 v[184:187], v233, s[4:5]
	s_add_u32 s16, s16, 0x4000
	v_add_u32_e32 v234, s16, v222
	global_load_dwordx4 v[188:191], v234, s[4:5]
	s_add_u32 s16, s16, 0x4000
	v_add_u32_e32 v231, s16, v222
	global_load_dwordx4 v[192:195], v231, s[4:5]
	s_add_u32 s16, s16, 0x4000
	v_add_u32_e32 v232, s16, v222
	global_load_dwordx4 v[196:199], v232, s[4:5]
	s_add_u32 s16, s16, 0x4000
	v_add_u32_e32 v233, s16, v222
	global_load_dwordx4 v[200:203], v233, s[4:5]
	s_add_u32 s16, s16, 0x4000
	v_add_u32_e32 v234, s16, v222
	global_load_dwordx4 v[204:207], v234, s[4:5]
	s_mul_i32 s16, s10, 0x88000
	s_add_u32 s16, s16, s14
	s_add_u32 s16, s16, 0x22000
	v_add_u32_e32 v231, s16, v221
	global_load_dwordx4 v[144:147], v231, s[2:3]
	s_add_u32 s16, s16, 0x4400
	v_add_u32_e32 v232, s16, v221
	global_load_dwordx4 v[148:151], v232, s[2:3]
	s_add_u32 s16, s16, 0x4400
	v_add_u32_e32 v233, s16, v221
	global_load_dwordx4 v[152:155], v233, s[2:3]
	s_add_u32 s16, s16, 0x4400
	v_add_u32_e32 v234, s16, v221
	global_load_dwordx4 v[156:159], v234, s[2:3]
	s_add_u32 s16, s16, 0x4400
	v_add_u32_e32 v231, s16, v221
	global_load_dwordx4 v[160:163], v231, s[2:3]
	s_add_u32 s16, s16, 0x4400
	v_add_u32_e32 v232, s16, v221
	global_load_dwordx4 v[164:167], v232, s[2:3]
	s_add_u32 s16, s16, 0x4400
	v_add_u32_e32 v233, s16, v221
	global_load_dwordx4 v[168:171], v233, s[2:3]
	s_add_u32 s16, s16, 0x4400
	v_add_u32_e32 v234, s16, v221
	global_load_dwordx4 v[172:175], v234, s[2:3]
	s_waitcnt lgkmcnt(0)
	s_barrier
	ds_read_b128 v[112:115], v225
	ds_read_b128 v[116:119], v225 offset:64
	ds_read_b128 v[120:123], v225 offset:128
	ds_read_b128 v[124:127], v225 offset:192
	ds_read_b128 v[128:131], v225 offset:256
	ds_read_b128 v[132:135], v225 offset:320
	ds_read_b128 v[136:139], v225 offset:384
	ds_read_b128 v[140:143], v225 offset:448
	s_waitcnt lgkmcnt(4)
	v_mfma_f32_16x16x32_bf16 v[96:99], v[112:115], v[0:3], 0
	v_mfma_f32_16x16x32_bf16 v[96:99], v[116:119], v[4:7], v[96:99]
	v_mfma_f32_16x16x32_bf16 v[96:99], v[120:123], v[8:11], v[96:99]
	v_mfma_f32_16x16x32_bf16 v[96:99], v[124:127], v[12:15], v[96:99]
	ds_read_b128 v[112:115], v225 offset:8448
	ds_read_b128 v[116:119], v225 offset:8512
	ds_read_b128 v[120:123], v225 offset:8576
	ds_read_b128 v[124:127], v225 offset:8640
	s_waitcnt lgkmcnt(4)
	v_mfma_f32_16x16x32_bf16 v[96:99], v[128:131], v[16:19], v[96:99]
	v_mfma_f32_16x16x32_bf16 v[96:99], v[132:135], v[20:23], v[96:99]
	v_mfma_f32_16x16x32_bf16 v[96:99], v[136:139], v[24:27], v[96:99]
	v_mfma_f32_16x16x32_bf16 v[96:99], v[140:143], v[28:31], v[96:99]
	ds_read_b128 v[128:131], v225 offset:8704
	ds_read_b128 v[132:135], v225 offset:8768
	ds_read_b128 v[136:139], v225 offset:8832
	ds_read_b128 v[140:143], v225 offset:8896
	s_waitcnt lgkmcnt(4)
	v_mfma_f32_16x16x32_bf16 v[100:103], v[112:115], v[0:3], 0
	v_mfma_f32_16x16x32_bf16 v[100:103], v[116:119], v[4:7], v[100:103]
	v_mfma_f32_16x16x32_bf16 v[100:103], v[120:123], v[8:11], v[100:103]
	v_mfma_f32_16x16x32_bf16 v[100:103], v[124:127], v[12:15], v[100:103]
	ds_read_b128 v[112:115], v225 offset:16896
	ds_read_b128 v[116:119], v225 offset:16960
	ds_read_b128 v[120:123], v225 offset:17024
	ds_read_b128 v[124:127], v225 offset:17088
	s_waitcnt lgkmcnt(4)
; DEVI unsigned pack2(float a, float b) { return (unsigned)f2bf(a) | ((unsigned)f2bf(b) << 16); }
; DEVI float fexp2(float x) { return __builtin_amdgcn_exp2f(x); }
; template <int DH, int NQ, int LDK, class MaskF>
; DEVI void attn_qk(const u16* sK, const bf16x8 (&qf)[NQ][DH / 32], f32x4 (&o)[NQ][DH / 16], float (&m)[NQ], float (&l)[NQ],
;                   float c2, int lane, MaskF valid, bf16x8 (&pb)[NQ][2]) {
;     ...
; #pragma unroll
;   for (int qt = 0; qt < NQ; ++qt) {
;     float mx = -1e30f;
; #pragma unroll
;     for (int kt = 0; kt < 4; ++kt)
; #pragma unroll
;       for (int r = 0; r < 4; ++r) {
;         const bool v = valid(qt, 16 * kt + 4 * quad + r);
;         const float sv = v ? s[qt][kt][r] : -1e30f;
;         s[qt][kt][r] = sv;
;         mx = fmaxf(mx, sv);
;       }
;     mx = fmaxf(mx, __shfl_xor(mx, 16));
;     mx = fmaxf(mx, __shfl_xor(mx, 32));
;     const float mn = fmaxf(m[qt], mx);
;     const float alpha = fexp2((m[qt] - mn) * c2);
;     m[qt] = mn;
;     const float mc = fmaxf(mn, -1e20f) * c2;
;     float ps = 0.f;
; #pragma unroll
;     for (int kt = 0; kt < 4; ++kt)
; #pragma unroll
;       for (int r = 0; r < 4; ++r) {
;         const float pv = fexp2(__builtin_fmaf(s[qt][kt][r], c2, -mc));
;         ps += pv;
;         s[qt][kt][r] = pv;
;       }
;     l[qt] = l[qt] * alpha + ps;
; #pragma unroll
;     for (int dt = 0; dt < DH / 16; ++dt) o[qt][dt] *= alpha;
; #pragma unroll
;     for (int kk = 0; kk < 2; ++kk) {
;       union { bf16x8 v; unsigned u[4]; } cv;
;       cv.u[0] = pack2(s[qt][2 * kk][0], s[qt][2 * kk][1]);
;       cv.u[1] = pack2(s[qt][2 * kk][2], s[qt][2 * kk][3]);
;       cv.u[2] = pack2(s[qt][2 * kk + 1][0], s[qt][2 * kk + 1][1]);
;       cv.u[3] = pack2(s[qt][2 * kk + 1][2], s[qt][2 * kk + 1][3]);
;       pb[qt][kk] = cv.v;
;     }
;   }
	v_mfma_f32_16x16x32_bf16 v[100:103], v[128:131], v[16:19], v[100:103]
	v_mfma_f32_16x16x32_bf16 v[100:103], v[132:135], v[20:23], v[100:103]
	v_mfma_f32_16x16x32_bf16 v[100:103], v[136:139], v[24:27], v[100:103]
	v_mfma_f32_16x16x32_bf16 v[100:103], v[140:143], v[28:31], v[100:103]
	ds_read_b128 v[128:131], v225 offset:17152
	ds_read_b128 v[132:135], v225 offset:17216
	ds_read_b128 v[136:139], v225 offset:17280
	ds_read_b128 v[140:143], v225 offset:17344
	s_waitcnt lgkmcnt(4)
	v_mfma_f32_16x16x32_bf16 v[104:107], v[112:115], v[0:3], 0
	v_mfma_f32_16x16x32_bf16 v[104:107], v[116:119], v[4:7], v[104:107]
	v_mfma_f32_16x16x32_bf16 v[104:107], v[120:123], v[8:11], v[104:107]
	v_mfma_f32_16x16x32_bf16 v[104:107], v[124:127], v[12:15], v[104:107]
	ds_read_b128 v[112:115], v225 offset:25344
	ds_read_b128 v[116:119], v225 offset:25408
	ds_read_b128 v[120:123], v225 offset:25472
	ds_read_b128 v[124:127], v225 offset:25536
	s_waitcnt lgkmcnt(4)
	v_mfma_f32_16x16x32_bf16 v[104:107], v[128:131], v[16:19], v[104:107]
	v_mfma_f32_16x16x32_bf16 v[104:107], v[132:135], v[20:23], v[104:107]
	v_mfma_f32_16x16x32_bf16 v[104:107], v[136:139], v[24:27], v[104:107]
	v_mfma_f32_16x16x32_bf16 v[104:107], v[140:143], v[28:31], v[104:107]
	ds_read_b128 v[128:131], v225 offset:25600
	ds_read_b128 v[132:135], v225 offset:25664
	ds_read_b128 v[136:139], v225 offset:25728
	ds_read_b128 v[140:143], v225 offset:25792
	s_waitcnt lgkmcnt(4)
	v_mfma_f32_16x16x32_bf16 v[108:111], v[112:115], v[0:3], 0
	v_mfma_f32_16x16x32_bf16 v[108:111], v[116:119], v[4:7], v[108:111]
	v_mfma_f32_16x16x32_bf16 v[108:111], v[120:123], v[8:11], v[108:111]
	v_mfma_f32_16x16x32_bf16 v[108:111], v[124:127], v[12:15], v[108:111]
	s_waitcnt lgkmcnt(0)
	v_mfma_f32_16x16x32_bf16 v[108:111], v[128:131], v[16:19], v[108:111]
	v_mfma_f32_16x16x32_bf16 v[108:111], v[132:135], v[20:23], v[108:111]
	v_mfma_f32_16x16x32_bf16 v[108:111], v[136:139], v[24:27], v[108:111]
	v_mfma_f32_16x16x32_bf16 v[108:111], v[140:143], v[28:31], v[108:111]
	s_nop 7
	v_max3_f32 v235, v96, v97, v98
	v_max3_f32 v235, v235, v99, v100
	v_max3_f32 v235, v235, v101, v102
	v_max3_f32 v235, v235, v103, v104
	v_max3_f32 v235, v235, v105, v106
	v_max3_f32 v235, v235, v107, v108
	v_max3_f32 v235, v235, v109, v110
	v_max_f32_e32 v235, v111, v235
	ds_bpermute_b32 v236, v228, v235
	s_waitcnt lgkmcnt(0)
	v_max_f32_e32 v235, v236, v235
	v_mov_b32_e32 v236, v235
	v_mov_b32_e32 v237, v235
	s_nop 1
	v_permlane32_swap_b32_e32 v236, v237
	v_max_f32_e32 v235, v236, v237
	v_max_f32_e32 v238, v229, v235
	v_sub_f32_e32 v239, v229, v238
	v_mul_f32_e32 v239, 0x3db8aa3b, v239
	v_exp_f32_e32 v239, v239
	v_mov_b32_e32 v229, v238
	v_mul_f32_e32 v240, 0xbdb8aa3b, v238
	v_fma_f32 v96, v96, v242, v240
	v_exp_f32_e32 v96, v96
	v_fma_f32 v97, v97, v242, v240
	v_exp_f32_e32 v97, v97
	v_fma_f32 v98, v98, v242, v240
	v_exp_f32_e32 v98, v98
	v_fma_f32 v99, v99, v242, v240
	v_exp_f32_e32 v99, v99
	v_fma_f32 v100, v100, v242, v240
	v_exp_f32_e32 v100, v100
	v_fma_f32 v101, v101, v242, v240
	v_exp_f32_e32 v101, v101
	v_fma_f32 v102, v102, v242, v240
	v_exp_f32_e32 v102, v102
	v_fma_f32 v103, v103, v242, v240
	v_exp_f32_e32 v103, v103
	v_fma_f32 v104, v104, v242, v240
	v_exp_f32_e32 v104, v104
	v_fma_f32 v105, v105, v242, v240
	v_exp_f32_e32 v105, v105
	v_fma_f32 v106, v106, v242, v240
	v_exp_f32_e32 v106, v106
	v_fma_f32 v107, v107, v242, v240
	v_exp_f32_e32 v107, v107
	v_fma_f32 v108, v108, v242, v240
	v_exp_f32_e32 v108, v108
	v_fma_f32 v109, v109, v242, v240
	v_exp_f32_e32 v109, v109
	v_fma_f32 v110, v110, v242, v240
	v_exp_f32_e32 v110, v110
	v_fma_f32 v111, v111, v242, v240
	v_exp_f32_e32 v111, v111
	s_nop 0
	v_add_f32_e32 v241, v96, v97
	v_add_f32_e32 v241, v98, v241
	v_add_f32_e32 v241, v99, v241
	v_add_f32_e32 v241, v100, v241
	v_add_f32_e32 v241, v101, v241
	v_add_f32_e32 v241, v102, v241
	v_add_f32_e32 v241, v103, v241
	v_add_f32_e32 v241, v104, v241
	v_add_f32_e32 v241, v105, v241
	v_add_f32_e32 v241, v106, v241
	v_add_f32_e32 v241, v107, v241
	v_add_f32_e32 v241, v108, v241
	v_add_f32_e32 v241, v109, v241
	v_add_f32_e32 v241, v110, v241
	v_add_f32_e32 v241, v111, v241
	v_fma_f32 v230, v230, v239, v241
	v_cvt_pk_bf16_f32 v212, v96, v97
	v_cvt_pk_bf16_f32 v213, v98, v99
	v_cvt_pk_bf16_f32 v214, v100, v101
	v_cvt_pk_bf16_f32 v215, v102, v103
	v_cvt_pk_bf16_f32 v216, v104, v105
	v_cvt_pk_bf16_f32 v217, v106, v107
	v_cvt_pk_bf16_f32 v218, v108, v109
	v_cvt_pk_bf16_f32 v219, v110, v111
	s_waitcnt vmcnt(8)
	ds_write_b128 v224, v[176:179]
	ds_write_b128 v224, v[180:183] offset:4608
	ds_write_b128 v224, v[184:187] offset:9216
	ds_write_b128 v224, v[188:191] offset:13824
	ds_write_b128 v224, v[192:195] offset:18432
	ds_write_b128 v224, v[196:199] offset:23040
	ds_write_b128 v224, v[200:203] offset:27648
	ds_write_b128 v224, v[204:207] offset:32256
	s_waitcnt lgkmcnt(0)
	s_barrier
; DEVI f32x4 mfma16(bf16x8 a, bf16x8 b, f32x4 c) { return __builtin_amdgcn_mfma_f32_16x16x32_bf16(a, b, c, 0, 0, 0); }
; #define STOREK_() SK1_(0) SK1_(1) SK1_(2) SK1_(3) SK1_(4) SK1_(5) SK1_(6) SK1_(7)
; #define LOADV_(kbx) LV1_(0, kbx) LV1_(1, kbx) LV1_(2, kbx) LV1_(3, kbx) LV1_(4, kbx) LV1_(5, kbx) LV1_(6, kbx) LV1_(7, kbx)
; template <int DH, int NQ, int LDV>
; DEVI void attn_pv(const u16* sVt, const bf16x8 (&pb)[NQ][2], f32x4 (&o)[NQ][DH / 16], int lane) {
;   const int col = lane & 15, quad = lane >> 4;
;   __builtin_amdgcn_s_setprio(1);
; #pragma unroll
;   for (int dt = 0; dt < DH / 16; ++dt) {
; #pragma unroll
;     for (int kk = 0; kk < 2; ++kk) {
;       union { bf16x8 v; uint2 h[2]; } cv;
;       cv.h[0] = *(const uint2*)(sVt + (16 * dt + col) * LDV + 32 * kk + 4 * quad);
;       cv.h[1] = *(const uint2*)(sVt + (16 * dt + col) * LDV + 32 * kk + 16 + 4 * quad);
; #pragma unroll
;       for (int qt = 0; qt < NQ; ++qt) o[qt][dt] = mfma16(cv.v, pb[qt][kk], o[qt][dt]);
;     }
;   }
;   __builtin_amdgcn_s_setprio(0);
; }
; DEVI void phase_memattn(const Params& p, unsigned char* smem) {
;     ...
;       if (kb < 3) {
;         STOREK_()
;         LOADV_(kb + 1)
	s_lshl_b32 s16, s10, 2
	s_add_u32 s16, s16, s11
	s_lshl_b32 s16, s16, 17
	s_add_u32 s16, s16, 128
	v_add_u32_e32 v231, s16, v222
	global_load_dwordx4 v[176:179], v231, s[4:5]
	s_add_u32 s16, s16, 0x4000
	v_add_u32_e32 v232, s16, v222
	global_load_dwordx4 v[180:183], v232, s[4:5]
	s_add_u32 s16, s16, 0x4000
	v_add_u32_e32 v233, s16, v222
	global_load_dwordx4 v[184:187], v233, s[4:5]
	s_add_u32 s16, s16, 0x4000
	v_add_u32_e32 v234, s16, v222
	global_load_dwordx4 v[188:191], v234, s[4:5]
	s_add_u32 s16, s16, 0x4000
	v_add_u32_e32 v231, s16, v222
	global_load_dwordx4 v[192:195], v231, s[4:5]
	s_add_u32 s16, s16, 0x4000
	v_add_u32_e32 v232, s16, v222
	global_load_dwordx4 v[196:199], v232, s[4:5]
	s_add_u32 s16, s16, 0x4000
	v_add_u32_e32 v233, s16, v222
	global_load_dwordx4 v[200:203], v233, s[4:5]
	s_add_u32 s16, s16, 0x4000
	v_add_u32_e32 v234, s16, v222
	global_load_dwordx4 v[204:207], v234, s[4:5]
	ds_read_b64 v[112:113], v226 offset:0
	ds_read_b64 v[114:115], v226 offset:32
	ds_read_b64 v[116:117], v226 offset:64
	ds_read_b64 v[118:119], v226 offset:96
	ds_read_b64 v[120:121], v226 offset:2304
	ds_read_b64 v[122:123], v226 offset:2336
	ds_read_b64 v[124:125], v226 offset:2368
	ds_read_b64 v[126:127], v226 offset:2400
	ds_read_b64 v[128:129], v226 offset:4608
	ds_read_b64 v[130:131], v226 offset:4640
	ds_read_b64 v[132:133], v226 offset:4672
	ds_read_b64 v[134:135], v226 offset:4704
	ds_read_b64 v[136:137], v226 offset:6912
	ds_read_b64 v[138:139], v226 offset:6944
	ds_read_b64 v[140:141], v226 offset:6976
	ds_read_b64 v[142:143], v226 offset:7008
	s_waitcnt lgkmcnt(14)
	v_mfma_f32_16x16x32_bf16 v[32:35], v[112:115], v[212:215], 0
	ds_read_b64 v[112:113], v226 offset:9216
	ds_read_b64 v[114:115], v226 offset:9248
	s_waitcnt lgkmcnt(14)
	v_mfma_f32_16x16x32_bf16 v[32:35], v[116:119], v[216:219], v[32:35]
	ds_read_b64 v[116:117], v226 offset:9280
	ds_read_b64 v[118:119], v226 offset:9312
	s_waitcnt lgkmcnt(14)
	v_mfma_f32_16x16x32_bf16 v[36:39], v[120:123], v[212:215], 0
	ds_read_b64 v[120:121], v226 offset:11520
	ds_read_b64 v[122:123], v226 offset:11552
	s_waitcnt lgkmcnt(14)
	v_mfma_f32_16x16x32_bf16 v[36:39], v[124:127], v[216:219], v[36:39]
	ds_read_b64 v[124:125], v226 offset:11584
	ds_read_b64 v[126:127], v226 offset:11616
	s_waitcnt lgkmcnt(14)
	v_mfma_f32_16x16x32_bf16 v[40:43], v[128:131], v[212:215], 0
	ds_read_b64 v[128:129], v226 offset:13824
	ds_read_b64 v[130:131], v226 offset:13856
	s_waitcnt lgkmcnt(14)
	v_mfma_f32_16x16x32_bf16 v[40:43], v[132:135], v[216:219], v[40:43]
	ds_read_b64 v[132:133], v226 offset:13888
	ds_read_b64 v[134:135], v226 offset:13920
	s_waitcnt lgkmcnt(14)
	v_mfma_f32_16x16x32_bf16 v[44:47], v[136:139], v[212:215], 0
	ds_read_b64 v[136:137], v226 offset:16128
	ds_read_b64 v[138:139], v226 offset:16160
	s_waitcnt lgkmcnt(14)
	v_mfma_f32_16x16x32_bf16 v[44:47], v[140:143], v[216:219], v[44:47]
	ds_read_b64 v[140:141], v226 offset:16192
	ds_read_b64 v[142:143], v226 offset:16224
	s_waitcnt lgkmcnt(14)
	v_mfma_f32_16x16x32_bf16 v[48:51], v[112:115], v[212:215], 0
	ds_read_b64 v[112:113], v226 offset:18432
	ds_read_b64 v[114:115], v226 offset:18464
	s_waitcnt lgkmcnt(14)
	v_mfma_f32_16x16x32_bf16 v[48:51], v[116:119], v[216:219], v[48:51]
	ds_read_b64 v[116:117], v226 offset:18496
	ds_read_b64 v[118:119], v226 offset:18528
	s_waitcnt lgkmcnt(14)
	v_mfma_f32_16x16x32_bf16 v[52:55], v[120:123], v[212:215], 0
	ds_read_b64 v[120:121], v226 offset:20736
	ds_read_b64 v[122:123], v226 offset:20768
	s_waitcnt lgkmcnt(14)
	v_mfma_f32_16x16x32_bf16 v[52:55], v[124:127], v[216:219], v[52:55]
	ds_read_b64 v[124:125], v226 offset:20800
	ds_read_b64 v[126:127], v226 offset:20832
	s_waitcnt lgkmcnt(14)
	v_mfma_f32_16x16x32_bf16 v[56:59], v[128:131], v[212:215], 0
	ds_read_b64 v[128:129], v226 offset:23040
	ds_read_b64 v[130:131], v226 offset:23072
	s_waitcnt lgkmcnt(14)
	v_mfma_f32_16x16x32_bf16 v[56:59], v[132:135], v[216:219], v[56:59]
	ds_read_b64 v[132:133], v226 offset:23104
	ds_read_b64 v[134:135], v226 offset:23136
	s_waitcnt lgkmcnt(14)
	v_mfma_f32_16x16x32_bf16 v[60:63], v[136:139], v[212:215], 0
	ds_read_b64 v[136:137], v226 offset:25344
	ds_read_b64 v[138:139], v226 offset:25376
	s_waitcnt lgkmcnt(14)
	v_mfma_f32_16x16x32_bf16 v[60:63], v[140:143], v[216:219], v[60:63]
	ds_read_b64 v[140:141], v226 offset:25408
	ds_read_b64 v[142:143], v226 offset:25440
	s_waitcnt lgkmcnt(14)
	v_mfma_f32_16x16x32_bf16 v[64:67], v[112:115], v[212:215], 0
	ds_read_b64 v[112:113], v226 offset:27648
	ds_read_b64 v[114:115], v226 offset:27680
	s_waitcnt lgkmcnt(14)
	v_mfma_f32_16x16x32_bf16 v[64:67], v[116:119], v[216:219], v[64:67]
	ds_read_b64 v[116:117], v226 offset:27712
	ds_read_b64 v[118:119], v226 offset:27744
	s_waitcnt lgkmcnt(14)
	v_mfma_f32_16x16x32_bf16 v[68:71], v[120:123], v[212:215], 0
	ds_read_b64 v[120:121], v226 offset:29952
	ds_read_b64 v[122:123], v226 offset:29984
	s_waitcnt lgkmcnt(14)
	v_mfma_f32_16x16x32_bf16 v[68:71], v[124:127], v[216:219], v[68:71]
	ds_read_b64 v[124:125], v226 offset:30016
	ds_read_b64 v[126:127], v226 offset:30048
	s_waitcnt lgkmcnt(14)
	v_mfma_f32_16x16x32_bf16 v[72:75], v[128:131], v[212:215], 0
	ds_read_b64 v[128:129], v226 offset:32256
	ds_read_b64 v[130:131], v226 offset:32288
	s_waitcnt lgkmcnt(14)
	v_mfma_f32_16x16x32_bf16 v[72:75], v[132:135], v[216:219], v[72:75]
	ds_read_b64 v[132:133], v226 offset:32320
	ds_read_b64 v[134:135], v226 offset:32352
	s_waitcnt lgkmcnt(14)
	v_mfma_f32_16x16x32_bf16 v[76:79], v[136:139], v[212:215], 0
	ds_read_b64 v[136:137], v226 offset:34560
	ds_read_b64 v[138:139], v226 offset:34592
	s_waitcnt lgkmcnt(14)
; DEVI f32x4 mfma16(bf16x8 a, bf16x8 b, f32x4 c) { return __builtin_amdgcn_mfma_f32_16x16x32_bf16(a, b, c, 0, 0, 0); }
; #define STOREK_() SK1_(0) SK1_(1) SK1_(2) SK1_(3) SK1_(4) SK1_(5) SK1_(6) SK1_(7)
; #define LOADV_(kbx) LV1_(0, kbx) LV1_(1, kbx) LV1_(2, kbx) LV1_(3, kbx) LV1_(4, kbx) LV1_(5, kbx) LV1_(6, kbx) LV1_(7, kbx)
; template <int DH, int NQ, int LDK, class MaskF>
; DEVI void attn_qk(const u16* sK, const bf16x8 (&qf)[NQ][DH / 32], f32x4 (&o)[NQ][DH / 16], float (&m)[NQ], float (&l)[NQ],
;                   float c2, int lane, MaskF valid, bf16x8 (&pb)[NQ][2]) {
;     ...
;   for (int kt = 0; kt < 4; ++kt) {
; #pragma unroll
;     for (int qt = 0; qt < NQ; ++qt) s[qt][kt] = f32x4{0.f, 0.f, 0.f, 0.f};
; #pragma unroll
;     for (int ks = 0; ks < DH / 32; ++ks) {
;       const bf16x8 kf = *(const bf16x8*)(sK + (16 * kt + col) * LDK + 32 * ks + 8 * quad);
; #pragma unroll
;       for (int qt = 0; qt < NQ; ++qt) s[qt][kt] = mfma16(kf, qf[qt][ks], s[qt][kt]);
;     }
;   }
; DEVI void phase_memattn(const Params& p, unsigned char* smem) {
;     ...
;       if (kb < 3) {
;         STOREK_()
;         LOADV_(kb + 1)
;       }
;       __syncthreads();
;     }
	v_mfma_f32_16x16x32_bf16 v[76:79], v[140:143], v[216:219], v[76:79]
	ds_read_b64 v[140:141], v226 offset:34624
	ds_read_b64 v[142:143], v226 offset:34656
	s_waitcnt lgkmcnt(14)
	v_mfma_f32_16x16x32_bf16 v[80:83], v[112:115], v[212:215], 0
	s_waitcnt lgkmcnt(12)
	v_mfma_f32_16x16x32_bf16 v[80:83], v[116:119], v[216:219], v[80:83]
	s_waitcnt lgkmcnt(10)
	v_mfma_f32_16x16x32_bf16 v[84:87], v[120:123], v[212:215], 0
	s_waitcnt lgkmcnt(8)
	v_mfma_f32_16x16x32_bf16 v[84:87], v[124:127], v[216:219], v[84:87]
	s_waitcnt lgkmcnt(6)
	v_mfma_f32_16x16x32_bf16 v[88:91], v[128:131], v[212:215], 0
	s_waitcnt lgkmcnt(4)
	v_mfma_f32_16x16x32_bf16 v[88:91], v[132:135], v[216:219], v[88:91]
	s_waitcnt lgkmcnt(2)
	v_mfma_f32_16x16x32_bf16 v[92:95], v[136:139], v[212:215], 0
	s_waitcnt lgkmcnt(0)
	v_mfma_f32_16x16x32_bf16 v[92:95], v[140:143], v[216:219], v[92:95]
	s_waitcnt vmcnt(8)
	ds_write_b128 v223, v[144:147]
	ds_write_b128 v223, v[148:151] offset:4224
	ds_write_b128 v223, v[152:155] offset:8448
	ds_write_b128 v223, v[156:159] offset:12672
	ds_write_b128 v223, v[160:163] offset:16896
	ds_write_b128 v223, v[164:167] offset:21120
	ds_write_b128 v223, v[168:171] offset:25344
	ds_write_b128 v223, v[172:175] offset:29568
	s_mul_i32 s16, s10, 0x88000
	s_add_u32 s16, s16, s14
	s_add_u32 s16, s16, 0x44000
	v_add_u32_e32 v231, s16, v221
	global_load_dwordx4 v[144:147], v231, s[2:3]
	s_add_u32 s16, s16, 0x4400
	v_add_u32_e32 v232, s16, v221
	global_load_dwordx4 v[148:151], v232, s[2:3]
	s_add_u32 s16, s16, 0x4400
	v_add_u32_e32 v233, s16, v221
	global_load_dwordx4 v[152:155], v233, s[2:3]
	s_add_u32 s16, s16, 0x4400
	v_add_u32_e32 v234, s16, v221
	global_load_dwordx4 v[156:159], v234, s[2:3]
	s_add_u32 s16, s16, 0x4400
	v_add_u32_e32 v231, s16, v221
	global_load_dwordx4 v[160:163], v231, s[2:3]
	s_add_u32 s16, s16, 0x4400
	v_add_u32_e32 v232, s16, v221
	global_load_dwordx4 v[164:167], v232, s[2:3]
	s_add_u32 s16, s16, 0x4400
	v_add_u32_e32 v233, s16, v221
	global_load_dwordx4 v[168:171], v233, s[2:3]
	s_add_u32 s16, s16, 0x4400
	v_add_u32_e32 v234, s16, v221
	global_load_dwordx4 v[172:175], v234, s[2:3]
	s_waitcnt lgkmcnt(0)
	s_barrier
	ds_read_b128 v[112:115], v225
	ds_read_b128 v[116:119], v225 offset:64
	ds_read_b128 v[120:123], v225 offset:128
	ds_read_b128 v[124:127], v225 offset:192
	ds_read_b128 v[128:131], v225 offset:256
	ds_read_b128 v[132:135], v225 offset:320
	ds_read_b128 v[136:139], v225 offset:384
	ds_read_b128 v[140:143], v225 offset:448
	s_waitcnt lgkmcnt(4)
	v_mfma_f32_16x16x32_bf16 v[96:99], v[112:115], v[0:3], 0
	v_mfma_f32_16x16x32_bf16 v[96:99], v[116:119], v[4:7], v[96:99]
	v_mfma_f32_16x16x32_bf16 v[96:99], v[120:123], v[8:11], v[96:99]
	v_mfma_f32_16x16x32_bf16 v[96:99], v[124:127], v[12:15], v[96:99]
	ds_read_b128 v[112:115], v225 offset:8448
	ds_read_b128 v[116:119], v225 offset:8512
	ds_read_b128 v[120:123], v225 offset:8576
	ds_read_b128 v[124:127], v225 offset:8640
	s_waitcnt lgkmcnt(4)
	v_mfma_f32_16x16x32_bf16 v[96:99], v[128:131], v[16:19], v[96:99]
	v_mfma_f32_16x16x32_bf16 v[96:99], v[132:135], v[20:23], v[96:99]
	v_mfma_f32_16x16x32_bf16 v[96:99], v[136:139], v[24:27], v[96:99]
	v_mfma_f32_16x16x32_bf16 v[96:99], v[140:143], v[28:31], v[96:99]
	ds_read_b128 v[128:131], v225 offset:8704
	ds_read_b128 v[132:135], v225 offset:8768
	ds_read_b128 v[136:139], v225 offset:8832
	ds_read_b128 v[140:143], v225 offset:8896
	s_waitcnt lgkmcnt(4)
	v_mfma_f32_16x16x32_bf16 v[100:103], v[112:115], v[0:3], 0
	v_mfma_f32_16x16x32_bf16 v[100:103], v[116:119], v[4:7], v[100:103]
	v_mfma_f32_16x16x32_bf16 v[100:103], v[120:123], v[8:11], v[100:103]
	v_mfma_f32_16x16x32_bf16 v[100:103], v[124:127], v[12:15], v[100:103]
	ds_read_b128 v[112:115], v225 offset:16896
	ds_read_b128 v[116:119], v225 offset:16960
	ds_read_b128 v[120:123], v225 offset:17024
	ds_read_b128 v[124:127], v225 offset:17088
	s_waitcnt lgkmcnt(4)
	v_mfma_f32_16x16x32_bf16 v[100:103], v[128:131], v[16:19], v[100:103]
	v_mfma_f32_16x16x32_bf16 v[100:103], v[132:135], v[20:23], v[100:103]
	v_mfma_f32_16x16x32_bf16 v[100:103], v[136:139], v[24:27], v[100:103]
	v_mfma_f32_16x16x32_bf16 v[100:103], v[140:143], v[28:31], v[100:103]
	ds_read_b128 v[128:131], v225 offset:17152
	ds_read_b128 v[132:135], v225 offset:17216
	ds_read_b128 v[136:139], v225 offset:17280
	ds_read_b128 v[140:143], v225 offset:17344
	s_waitcnt lgkmcnt(4)
	v_mfma_f32_16x16x32_bf16 v[104:107], v[112:115], v[0:3], 0
	v_mfma_f32_16x16x32_bf16 v[104:107], v[116:119], v[4:7], v[104:107]
	v_mfma_f32_16x16x32_bf16 v[104:107], v[120:123], v[8:11], v[104:107]
	v_mfma_f32_16x16x32_bf16 v[104:107], v[124:127], v[12:15], v[104:107]
	ds_read_b128 v[112:115], v225 offset:25344
	ds_read_b128 v[116:119], v225 offset:25408
	ds_read_b128 v[120:123], v225 offset:25472
	ds_read_b128 v[124:127], v225 offset:25536
	s_waitcnt lgkmcnt(4)
	v_mfma_f32_16x16x32_bf16 v[104:107], v[128:131], v[16:19], v[104:107]
	v_mfma_f32_16x16x32_bf16 v[104:107], v[132:135], v[20:23], v[104:107]
	v_mfma_f32_16x16x32_bf16 v[104:107], v[136:139], v[24:27], v[104:107]
	v_mfma_f32_16x16x32_bf16 v[104:107], v[140:143], v[28:31], v[104:107]
	ds_read_b128 v[128:131], v225 offset:25600
	ds_read_b128 v[132:135], v225 offset:25664
	ds_read_b128 v[136:139], v225 offset:25728
	ds_read_b128 v[140:143], v225 offset:25792
	s_waitcnt lgkmcnt(4)
	v_mfma_f32_16x16x32_bf16 v[108:111], v[112:115], v[0:3], 0
	v_mfma_f32_16x16x32_bf16 v[108:111], v[116:119], v[4:7], v[108:111]
	v_mfma_f32_16x16x32_bf16 v[108:111], v[120:123], v[8:11], v[108:111]
	v_mfma_f32_16x16x32_bf16 v[108:111], v[124:127], v[12:15], v[108:111]
	s_waitcnt lgkmcnt(0)
; DEVI unsigned pack2(float a, float b) { return (unsigned)f2bf(a) | ((unsigned)f2bf(b) << 16); }
; DEVI float fexp2(float x) { return __builtin_amdgcn_exp2f(x); }
; template <int DH, int NQ, int LDK, class MaskF>
; DEVI void attn_qk(const u16* sK, const bf16x8 (&qf)[NQ][DH / 32], f32x4 (&o)[NQ][DH / 16], float (&m)[NQ], float (&l)[NQ],
;                   float c2, int lane, MaskF valid, bf16x8 (&pb)[NQ][2]) {
;     ...
; #pragma unroll
;   for (int qt = 0; qt < NQ; ++qt) {
;     float mx = -1e30f;
; #pragma unroll
;     for (int kt = 0; kt < 4; ++kt)
; #pragma unroll
;       for (int r = 0; r < 4; ++r) {
;         const bool v = valid(qt, 16 * kt + 4 * quad + r);
;         const float sv = v ? s[qt][kt][r] : -1e30f;
;         s[qt][kt][r] = sv;
;         mx = fmaxf(mx, sv);
;       }
;     mx = fmaxf(mx, __shfl_xor(mx, 16));
;     mx = fmaxf(mx, __shfl_xor(mx, 32));
;     const float mn = fmaxf(m[qt], mx);
;     const float alpha = fexp2((m[qt] - mn) * c2);
;     m[qt] = mn;
;     const float mc = fmaxf(mn, -1e20f) * c2;
;     float ps = 0.f;
; #pragma unroll
;     for (int kt = 0; kt < 4; ++kt)
; #pragma unroll
;       for (int r = 0; r < 4; ++r) {
;         const float pv = fexp2(__builtin_fmaf(s[qt][kt][r], c2, -mc));
;         ps += pv;
;         s[qt][kt][r] = pv;
;       }
;     l[qt] = l[qt] * alpha + ps;
; #pragma unroll
;     for (int dt = 0; dt < DH / 16; ++dt) o[qt][dt] *= alpha;
; #pragma unroll
;     for (int kk = 0; kk < 2; ++kk) {
;       union { bf16x8 v; unsigned u[4]; } cv;
;       cv.u[0] = pack2(s[qt][2 * kk][0], s[qt][2 * kk][1]);
;       cv.u[1] = pack2(s[qt][2 * kk][2], s[qt][2 * kk][3]);
;       cv.u[2] = pack2(s[qt][2 * kk + 1][0], s[qt][2 * kk + 1][1]);
;       cv.u[3] = pack2(s[qt][2 * kk + 1][2], s[qt][2 * kk + 1][3]);
;       pb[qt][kk] = cv.v;
;     }
;   }
	v_mfma_f32_16x16x32_bf16 v[108:111], v[128:131], v[16:19], v[108:111]
	v_mfma_f32_16x16x32_bf16 v[108:111], v[132:135], v[20:23], v[108:111]
	v_mfma_f32_16x16x32_bf16 v[108:111], v[136:139], v[24:27], v[108:111]
	v_mfma_f32_16x16x32_bf16 v[108:111], v[140:143], v[28:31], v[108:111]
	s_nop 7
	v_max3_f32 v235, v96, v97, v98
	v_max3_f32 v235, v235, v99, v100
	v_max3_f32 v235, v235, v101, v102
	v_max3_f32 v235, v235, v103, v104
	v_max3_f32 v235, v235, v105, v106
	v_max3_f32 v235, v235, v107, v108
	v_max3_f32 v235, v235, v109, v110
	v_max_f32_e32 v235, v111, v235
	ds_bpermute_b32 v236, v228, v235
	s_waitcnt lgkmcnt(0)
	v_max_f32_e32 v235, v236, v235
	v_mov_b32_e32 v236, v235
	v_mov_b32_e32 v237, v235
	s_nop 1
	v_permlane32_swap_b32_e32 v236, v237
	v_max_f32_e32 v235, v236, v237
	v_max_f32_e32 v238, v229, v235
	v_sub_f32_e32 v239, v229, v238
	v_mul_f32_e32 v239, 0x3db8aa3b, v239
	v_exp_f32_e32 v239, v239
	v_mov_b32_e32 v229, v238
	v_mul_f32_e32 v240, 0xbdb8aa3b, v238
	v_fma_f32 v96, v96, v242, v240
	v_exp_f32_e32 v96, v96
	v_fma_f32 v97, v97, v242, v240
	v_exp_f32_e32 v97, v97
	v_fma_f32 v98, v98, v242, v240
	v_exp_f32_e32 v98, v98
	v_fma_f32 v99, v99, v242, v240
	v_exp_f32_e32 v99, v99
	v_fma_f32 v100, v100, v242, v240
	v_exp_f32_e32 v100, v100
	v_fma_f32 v101, v101, v242, v240
	v_exp_f32_e32 v101, v101
	v_fma_f32 v102, v102, v242, v240
	v_exp_f32_e32 v102, v102
	v_fma_f32 v103, v103, v242, v240
	v_exp_f32_e32 v103, v103
	v_fma_f32 v104, v104, v242, v240
	v_exp_f32_e32 v104, v104
	v_fma_f32 v105, v105, v242, v240
	v_exp_f32_e32 v105, v105
	v_fma_f32 v106, v106, v242, v240
	v_exp_f32_e32 v106, v106
	v_fma_f32 v107, v107, v242, v240
	v_exp_f32_e32 v107, v107
	v_fma_f32 v108, v108, v242, v240
	v_exp_f32_e32 v108, v108
	v_fma_f32 v109, v109, v242, v240
	v_exp_f32_e32 v109, v109
	v_fma_f32 v110, v110, v242, v240
	v_exp_f32_e32 v110, v110
	v_fma_f32 v111, v111, v242, v240
	v_exp_f32_e32 v111, v111
	s_nop 0
	v_add_f32_e32 v241, v96, v97
	v_add_f32_e32 v241, v98, v241
	v_add_f32_e32 v241, v99, v241
	v_add_f32_e32 v241, v100, v241
	v_add_f32_e32 v241, v101, v241
	v_add_f32_e32 v241, v102, v241
	v_add_f32_e32 v241, v103, v241
	v_add_f32_e32 v241, v104, v241
	v_add_f32_e32 v241, v105, v241
	v_add_f32_e32 v241, v106, v241
	v_add_f32_e32 v241, v107, v241
	v_add_f32_e32 v241, v108, v241
	v_add_f32_e32 v241, v109, v241
	v_add_f32_e32 v241, v110, v241
	v_add_f32_e32 v241, v111, v241
	v_fma_f32 v230, v230, v239, v241
	v_mul_f32_e32 v32, v239, v32
	v_mul_f32_e32 v33, v239, v33
	v_mul_f32_e32 v34, v239, v34
	v_mul_f32_e32 v35, v239, v35
	v_mul_f32_e32 v36, v239, v36
	v_mul_f32_e32 v37, v239, v37
	v_mul_f32_e32 v38, v239, v38
	v_mul_f32_e32 v39, v239, v39
	v_mul_f32_e32 v40, v239, v40
	v_mul_f32_e32 v41, v239, v41
	v_mul_f32_e32 v42, v239, v42
	v_mul_f32_e32 v43, v239, v43
	v_mul_f32_e32 v44, v239, v44
	v_mul_f32_e32 v45, v239, v45
	v_mul_f32_e32 v46, v239, v46
	v_mul_f32_e32 v47, v239, v47
	v_mul_f32_e32 v48, v239, v48
	v_mul_f32_e32 v49, v239, v49
	v_mul_f32_e32 v50, v239, v50
	v_mul_f32_e32 v51, v239, v51
	v_mul_f32_e32 v52, v239, v52
	v_mul_f32_e32 v53, v239, v53
	v_mul_f32_e32 v54, v239, v54
	v_mul_f32_e32 v55, v239, v55
	v_mul_f32_e32 v56, v239, v56
	v_mul_f32_e32 v57, v239, v57
	v_mul_f32_e32 v58, v239, v58
	v_mul_f32_e32 v59, v239, v59
	v_mul_f32_e32 v60, v239, v60
	v_mul_f32_e32 v61, v239, v61
	v_mul_f32_e32 v62, v239, v62
	v_mul_f32_e32 v63, v239, v63
	v_mul_f32_e32 v64, v239, v64
	v_mul_f32_e32 v65, v239, v65
	v_mul_f32_e32 v66, v239, v66
	v_mul_f32_e32 v67, v239, v67
	v_mul_f32_e32 v68, v239, v68
	v_mul_f32_e32 v69, v239, v69
	v_mul_f32_e32 v70, v239, v70
	v_mul_f32_e32 v71, v239, v71
	v_mul_f32_e32 v72, v239, v72
	v_mul_f32_e32 v73, v239, v73
	v_mul_f32_e32 v74, v239, v74
	v_mul_f32_e32 v75, v239, v75
	v_mul_f32_e32 v76, v239, v76
	v_mul_f32_e32 v77, v239, v77
	v_mul_f32_e32 v78, v239, v78
	v_mul_f32_e32 v79, v239, v79
	v_mul_f32_e32 v80, v239, v80
	v_mul_f32_e32 v81, v239, v81
	v_mul_f32_e32 v82, v239, v82
	v_mul_f32_e32 v83, v239, v83
	v_mul_f32_e32 v84, v239, v84
	v_mul_f32_e32 v85, v239, v85
	v_mul_f32_e32 v86, v239, v86
	v_mul_f32_e32 v87, v239, v87
	v_mul_f32_e32 v88, v239, v88
	v_mul_f32_e32 v89, v239, v89
	v_mul_f32_e32 v90, v239, v90
	v_mul_f32_e32 v91, v239, v91
	v_mul_f32_e32 v92, v239, v92
	v_mul_f32_e32 v93, v239, v93
	v_mul_f32_e32 v94, v239, v94
	v_mul_f32_e32 v95, v239, v95
	v_cvt_pk_bf16_f32 v212, v96, v97
	v_cvt_pk_bf16_f32 v213, v98, v99
	v_cvt_pk_bf16_f32 v214, v100, v101
	v_cvt_pk_bf16_f32 v215, v102, v103
	v_cvt_pk_bf16_f32 v216, v104, v105
	v_cvt_pk_bf16_f32 v217, v106, v107
	v_cvt_pk_bf16_f32 v218, v108, v109
	v_cvt_pk_bf16_f32 v219, v110, v111
	s_waitcnt vmcnt(8)
	ds_write_b128 v224, v[176:179]
	ds_write_b128 v224, v[180:183] offset:4608
	ds_write_b128 v224, v[184:187] offset:9216
	ds_write_b128 v224, v[188:191] offset:13824
	ds_write_b128 v224, v[192:195] offset:18432
	ds_write_b128 v224, v[196:199] offset:23040
	ds_write_b128 v224, v[200:203] offset:27648
	ds_write_b128 v224, v[204:207] offset:32256
	s_waitcnt lgkmcnt(0)
	s_barrier
; DEVI f32x4 mfma16(bf16x8 a, bf16x8 b, f32x4 c) { return __builtin_amdgcn_mfma_f32_16x16x32_bf16(a, b, c, 0, 0, 0); }
; #define STOREK_() SK1_(0) SK1_(1) SK1_(2) SK1_(3) SK1_(4) SK1_(5) SK1_(6) SK1_(7)
; #define LOADV_(kbx) LV1_(0, kbx) LV1_(1, kbx) LV1_(2, kbx) LV1_(3, kbx) LV1_(4, kbx) LV1_(5, kbx) LV1_(6, kbx) LV1_(7, kbx)
; template <int DH, int NQ, int LDV>
; DEVI void attn_pv(const u16* sVt, const bf16x8 (&pb)[NQ][2], f32x4 (&o)[NQ][DH / 16], int lane) {
;   const int col = lane & 15, quad = lane >> 4;
;   __builtin_amdgcn_s_setprio(1);
; #pragma unroll
;   for (int dt = 0; dt < DH / 16; ++dt) {
; #pragma unroll
;     for (int kk = 0; kk < 2; ++kk) {
;       union { bf16x8 v; uint2 h[2]; } cv;
;       cv.h[0] = *(const uint2*)(sVt + (16 * dt + col) * LDV + 32 * kk + 4 * quad);
;       cv.h[1] = *(const uint2*)(sVt + (16 * dt + col) * LDV + 32 * kk + 16 + 4 * quad);
; #pragma unroll
;       for (int qt = 0; qt < NQ; ++qt) o[qt][dt] = mfma16(cv.v, pb[qt][kk], o[qt][dt]);
;     }
;   }
;   __builtin_amdgcn_s_setprio(0);
; }
; DEVI void phase_memattn(const Params& p, unsigned char* smem) {
;     ...
;       if (kb < 3) {
;         STOREK_()
;         LOADV_(kb + 1)
	s_lshl_b32 s16, s10, 2
	s_add_u32 s16, s16, s11
	s_lshl_b32 s16, s16, 17
	s_add_u32 s16, s16, 256
	v_add_u32_e32 v231, s16, v222
	global_load_dwordx4 v[176:179], v231, s[4:5]
	s_add_u32 s16, s16, 0x4000
	v_add_u32_e32 v232, s16, v222
	global_load_dwordx4 v[180:183], v232, s[4:5]
	s_add_u32 s16, s16, 0x4000
	v_add_u32_e32 v233, s16, v222
	global_load_dwordx4 v[184:187], v233, s[4:5]
	s_add_u32 s16, s16, 0x4000
	v_add_u32_e32 v234, s16, v222
	global_load_dwordx4 v[188:191], v234, s[4:5]
	s_add_u32 s16, s16, 0x4000
	v_add_u32_e32 v231, s16, v222
	global_load_dwordx4 v[192:195], v231, s[4:5]
	s_add_u32 s16, s16, 0x4000
	v_add_u32_e32 v232, s16, v222
	global_load_dwordx4 v[196:199], v232, s[4:5]
	s_add_u32 s16, s16, 0x4000
	v_add_u32_e32 v233, s16, v222
	global_load_dwordx4 v[200:203], v233, s[4:5]
	s_add_u32 s16, s16, 0x4000
	v_add_u32_e32 v234, s16, v222
	global_load_dwordx4 v[204:207], v234, s[4:5]
	ds_read_b64 v[112:113], v226 offset:0
	ds_read_b64 v[114:115], v226 offset:32
	ds_read_b64 v[116:117], v226 offset:64
	ds_read_b64 v[118:119], v226 offset:96
	ds_read_b64 v[120:121], v226 offset:2304
	ds_read_b64 v[122:123], v226 offset:2336
	ds_read_b64 v[124:125], v226 offset:2368
	ds_read_b64 v[126:127], v226 offset:2400
	ds_read_b64 v[128:129], v226 offset:4608
	ds_read_b64 v[130:131], v226 offset:4640
	ds_read_b64 v[132:133], v226 offset:4672
	ds_read_b64 v[134:135], v226 offset:4704
	ds_read_b64 v[136:137], v226 offset:6912
	ds_read_b64 v[138:139], v226 offset:6944
	ds_read_b64 v[140:141], v226 offset:6976
	ds_read_b64 v[142:143], v226 offset:7008
	s_waitcnt lgkmcnt(14)
	v_mfma_f32_16x16x32_bf16 v[32:35], v[112:115], v[212:215], v[32:35]
	ds_read_b64 v[112:113], v226 offset:9216
	ds_read_b64 v[114:115], v226 offset:9248
	s_waitcnt lgkmcnt(14)
	v_mfma_f32_16x16x32_bf16 v[32:35], v[116:119], v[216:219], v[32:35]
	ds_read_b64 v[116:117], v226 offset:9280
	ds_read_b64 v[118:119], v226 offset:9312
	s_waitcnt lgkmcnt(14)
	v_mfma_f32_16x16x32_bf16 v[36:39], v[120:123], v[212:215], v[36:39]
	ds_read_b64 v[120:121], v226 offset:11520
	ds_read_b64 v[122:123], v226 offset:11552
	s_waitcnt lgkmcnt(14)
	v_mfma_f32_16x16x32_bf16 v[36:39], v[124:127], v[216:219], v[36:39]
	ds_read_b64 v[124:125], v226 offset:11584
	ds_read_b64 v[126:127], v226 offset:11616
	s_waitcnt lgkmcnt(14)
	v_mfma_f32_16x16x32_bf16 v[40:43], v[128:131], v[212:215], v[40:43]
	ds_read_b64 v[128:129], v226 offset:13824
	ds_read_b64 v[130:131], v226 offset:13856
	s_waitcnt lgkmcnt(14)
	v_mfma_f32_16x16x32_bf16 v[40:43], v[132:135], v[216:219], v[40:43]
	ds_read_b64 v[132:133], v226 offset:13888
	ds_read_b64 v[134:135], v226 offset:13920
	s_waitcnt lgkmcnt(14)
	v_mfma_f32_16x16x32_bf16 v[44:47], v[136:139], v[212:215], v[44:47]
	ds_read_b64 v[136:137], v226 offset:16128
	ds_read_b64 v[138:139], v226 offset:16160
	s_waitcnt lgkmcnt(14)
	v_mfma_f32_16x16x32_bf16 v[44:47], v[140:143], v[216:219], v[44:47]
	ds_read_b64 v[140:141], v226 offset:16192
	ds_read_b64 v[142:143], v226 offset:16224
	s_waitcnt lgkmcnt(14)
	v_mfma_f32_16x16x32_bf16 v[48:51], v[112:115], v[212:215], v[48:51]
	ds_read_b64 v[112:113], v226 offset:18432
	ds_read_b64 v[114:115], v226 offset:18464
	s_waitcnt lgkmcnt(14)
	v_mfma_f32_16x16x32_bf16 v[48:51], v[116:119], v[216:219], v[48:51]
	ds_read_b64 v[116:117], v226 offset:18496
	ds_read_b64 v[118:119], v226 offset:18528
	s_waitcnt lgkmcnt(14)
	v_mfma_f32_16x16x32_bf16 v[52:55], v[120:123], v[212:215], v[52:55]
	ds_read_b64 v[120:121], v226 offset:20736
	ds_read_b64 v[122:123], v226 offset:20768
	s_waitcnt lgkmcnt(14)
	v_mfma_f32_16x16x32_bf16 v[52:55], v[124:127], v[216:219], v[52:55]
	ds_read_b64 v[124:125], v226 offset:20800
	ds_read_b64 v[126:127], v226 offset:20832
	s_waitcnt lgkmcnt(14)
	v_mfma_f32_16x16x32_bf16 v[56:59], v[128:131], v[212:215], v[56:59]
	ds_read_b64 v[128:129], v226 offset:23040
	ds_read_b64 v[130:131], v226 offset:23072
	s_waitcnt lgkmcnt(14)
	v_mfma_f32_16x16x32_bf16 v[56:59], v[132:135], v[216:219], v[56:59]
	ds_read_b64 v[132:133], v226 offset:23104
	ds_read_b64 v[134:135], v226 offset:23136
	s_waitcnt lgkmcnt(14)
	v_mfma_f32_16x16x32_bf16 v[60:63], v[136:139], v[212:215], v[60:63]
	ds_read_b64 v[136:137], v226 offset:25344
	ds_read_b64 v[138:139], v226 offset:25376
	s_waitcnt lgkmcnt(14)
	v_mfma_f32_16x16x32_bf16 v[60:63], v[140:143], v[216:219], v[60:63]
	ds_read_b64 v[140:141], v226 offset:25408
	ds_read_b64 v[142:143], v226 offset:25440
	s_waitcnt lgkmcnt(14)
	v_mfma_f32_16x16x32_bf16 v[64:67], v[112:115], v[212:215], v[64:67]
	ds_read_b64 v[112:113], v226 offset:27648
	ds_read_b64 v[114:115], v226 offset:27680
	s_waitcnt lgkmcnt(14)
	v_mfma_f32_16x16x32_bf16 v[64:67], v[116:119], v[216:219], v[64:67]
	ds_read_b64 v[116:117], v226 offset:27712
	ds_read_b64 v[118:119], v226 offset:27744
	s_waitcnt lgkmcnt(14)
	v_mfma_f32_16x16x32_bf16 v[68:71], v[120:123], v[212:215], v[68:71]
	ds_read_b64 v[120:121], v226 offset:29952
	ds_read_b64 v[122:123], v226 offset:29984
	s_waitcnt lgkmcnt(14)
	v_mfma_f32_16x16x32_bf16 v[68:71], v[124:127], v[216:219], v[68:71]
	ds_read_b64 v[124:125], v226 offset:30016
	ds_read_b64 v[126:127], v226 offset:30048
	s_waitcnt lgkmcnt(14)
	v_mfma_f32_16x16x32_bf16 v[72:75], v[128:131], v[212:215], v[72:75]
	ds_read_b64 v[128:129], v226 offset:32256
	ds_read_b64 v[130:131], v226 offset:32288
	s_waitcnt lgkmcnt(14)
	v_mfma_f32_16x16x32_bf16 v[72:75], v[132:135], v[216:219], v[72:75]
	ds_read_b64 v[132:133], v226 offset:32320
	ds_read_b64 v[134:135], v226 offset:32352
	s_waitcnt lgkmcnt(14)
	v_mfma_f32_16x16x32_bf16 v[76:79], v[136:139], v[212:215], v[76:79]
	ds_read_b64 v[136:137], v226 offset:34560
	ds_read_b64 v[138:139], v226 offset:34592
	s_waitcnt lgkmcnt(14)
; DEVI f32x4 mfma16(bf16x8 a, bf16x8 b, f32x4 c) { return __builtin_amdgcn_mfma_f32_16x16x32_bf16(a, b, c, 0, 0, 0); }
; #define STOREK_() SK1_(0) SK1_(1) SK1_(2) SK1_(3) SK1_(4) SK1_(5) SK1_(6) SK1_(7)
; #define LOADV_(kbx) LV1_(0, kbx) LV1_(1, kbx) LV1_(2, kbx) LV1_(3, kbx) LV1_(4, kbx) LV1_(5, kbx) LV1_(6, kbx) LV1_(7, kbx)
; template <int DH, int NQ, int LDK, class MaskF>
; DEVI void attn_qk(const u16* sK, const bf16x8 (&qf)[NQ][DH / 32], f32x4 (&o)[NQ][DH / 16], float (&m)[NQ], float (&l)[NQ],
;                   float c2, int lane, MaskF valid, bf16x8 (&pb)[NQ][2]) {
;     ...
;   for (int kt = 0; kt < 4; ++kt) {
; #pragma unroll
;     for (int qt = 0; qt < NQ; ++qt) s[qt][kt] = f32x4{0.f, 0.f, 0.f, 0.f};
; #pragma unroll
;     for (int ks = 0; ks < DH / 32; ++ks) {
;       const bf16x8 kf = *(const bf16x8*)(sK + (16 * kt + col) * LDK + 32 * ks + 8 * quad);
; #pragma unroll
;       for (int qt = 0; qt < NQ; ++qt) s[qt][kt] = mfma16(kf, qf[qt][ks], s[qt][kt]);
;     }
;   }
; DEVI void phase_memattn(const Params& p, unsigned char* smem) {
;     ...
;       if (kb < 3) {
;         STOREK_()
;         LOADV_(kb + 1)
;       }
;       __syncthreads();
;     }
	v_mfma_f32_16x16x32_bf16 v[76:79], v[140:143], v[216:219], v[76:79]
	ds_read_b64 v[140:141], v226 offset:34624
	ds_read_b64 v[142:143], v226 offset:34656
	s_waitcnt lgkmcnt(14)
	v_mfma_f32_16x16x32_bf16 v[80:83], v[112:115], v[212:215], v[80:83]
	s_waitcnt lgkmcnt(12)
	v_mfma_f32_16x16x32_bf16 v[80:83], v[116:119], v[216:219], v[80:83]
	s_waitcnt lgkmcnt(10)
	v_mfma_f32_16x16x32_bf16 v[84:87], v[120:123], v[212:215], v[84:87]
	s_waitcnt lgkmcnt(8)
	v_mfma_f32_16x16x32_bf16 v[84:87], v[124:127], v[216:219], v[84:87]
	s_waitcnt lgkmcnt(6)
	v_mfma_f32_16x16x32_bf16 v[88:91], v[128:131], v[212:215], v[88:91]
	s_waitcnt lgkmcnt(4)
	v_mfma_f32_16x16x32_bf16 v[88:91], v[132:135], v[216:219], v[88:91]
	s_waitcnt lgkmcnt(2)
	v_mfma_f32_16x16x32_bf16 v[92:95], v[136:139], v[212:215], v[92:95]
	s_waitcnt lgkmcnt(0)
	v_mfma_f32_16x16x32_bf16 v[92:95], v[140:143], v[216:219], v[92:95]
	s_waitcnt vmcnt(8)
	ds_write_b128 v223, v[144:147]
	ds_write_b128 v223, v[148:151] offset:4224
	ds_write_b128 v223, v[152:155] offset:8448
	ds_write_b128 v223, v[156:159] offset:12672
	ds_write_b128 v223, v[160:163] offset:16896
	ds_write_b128 v223, v[164:167] offset:21120
	ds_write_b128 v223, v[168:171] offset:25344
	ds_write_b128 v223, v[172:175] offset:29568
	s_mul_i32 s16, s10, 0x88000
	s_add_u32 s16, s16, s14
	s_add_u32 s16, s16, 0x66000
	v_add_u32_e32 v231, s16, v221
	global_load_dwordx4 v[144:147], v231, s[2:3]
	s_add_u32 s16, s16, 0x4400
	v_add_u32_e32 v232, s16, v221
	global_load_dwordx4 v[148:151], v232, s[2:3]
	s_add_u32 s16, s16, 0x4400
	v_add_u32_e32 v233, s16, v221
	global_load_dwordx4 v[152:155], v233, s[2:3]
	s_add_u32 s16, s16, 0x4400
	v_add_u32_e32 v234, s16, v221
	global_load_dwordx4 v[156:159], v234, s[2:3]
	s_add_u32 s16, s16, 0x4400
	v_add_u32_e32 v231, s16, v221
	global_load_dwordx4 v[160:163], v231, s[2:3]
	s_add_u32 s16, s16, 0x4400
	v_add_u32_e32 v232, s16, v221
	global_load_dwordx4 v[164:167], v232, s[2:3]
	s_add_u32 s16, s16, 0x4400
	v_add_u32_e32 v233, s16, v221
	global_load_dwordx4 v[168:171], v233, s[2:3]
	s_add_u32 s16, s16, 0x4400
	v_add_u32_e32 v234, s16, v221
	global_load_dwordx4 v[172:175], v234, s[2:3]
	s_waitcnt lgkmcnt(0)
	s_barrier
	ds_read_b128 v[112:115], v225
	ds_read_b128 v[116:119], v225 offset:64
	ds_read_b128 v[120:123], v225 offset:128
	ds_read_b128 v[124:127], v225 offset:192
	ds_read_b128 v[128:131], v225 offset:256
	ds_read_b128 v[132:135], v225 offset:320
	ds_read_b128 v[136:139], v225 offset:384
	ds_read_b128 v[140:143], v225 offset:448
	s_waitcnt lgkmcnt(4)
	v_mfma_f32_16x16x32_bf16 v[96:99], v[112:115], v[0:3], 0
	v_mfma_f32_16x16x32_bf16 v[96:99], v[116:119], v[4:7], v[96:99]
	v_mfma_f32_16x16x32_bf16 v[96:99], v[120:123], v[8:11], v[96:99]
	v_mfma_f32_16x16x32_bf16 v[96:99], v[124:127], v[12:15], v[96:99]
	ds_read_b128 v[112:115], v225 offset:8448
	ds_read_b128 v[116:119], v225 offset:8512
	ds_read_b128 v[120:123], v225 offset:8576
	ds_read_b128 v[124:127], v225 offset:8640
	s_waitcnt lgkmcnt(4)
	v_mfma_f32_16x16x32_bf16 v[96:99], v[128:131], v[16:19], v[96:99]
	v_mfma_f32_16x16x32_bf16 v[96:99], v[132:135], v[20:23], v[96:99]
	v_mfma_f32_16x16x32_bf16 v[96:99], v[136:139], v[24:27], v[96:99]
	v_mfma_f32_16x16x32_bf16 v[96:99], v[140:143], v[28:31], v[96:99]
	ds_read_b128 v[128:131], v225 offset:8704
	ds_read_b128 v[132:135], v225 offset:8768
	ds_read_b128 v[136:139], v225 offset:8832
	ds_read_b128 v[140:143], v225 offset:8896
	s_waitcnt lgkmcnt(4)
	v_mfma_f32_16x16x32_bf16 v[100:103], v[112:115], v[0:3], 0
	v_mfma_f32_16x16x32_bf16 v[100:103], v[116:119], v[4:7], v[100:103]
	v_mfma_f32_16x16x32_bf16 v[100:103], v[120:123], v[8:11], v[100:103]
	v_mfma_f32_16x16x32_bf16 v[100:103], v[124:127], v[12:15], v[100:103]
	ds_read_b128 v[112:115], v225 offset:16896
	ds_read_b128 v[116:119], v225 offset:16960
	ds_read_b128 v[120:123], v225 offset:17024
	ds_read_b128 v[124:127], v225 offset:17088
	s_waitcnt lgkmcnt(4)
	v_mfma_f32_16x16x32_bf16 v[100:103], v[128:131], v[16:19], v[100:103]
	v_mfma_f32_16x16x32_bf16 v[100:103], v[132:135], v[20:23], v[100:103]
	v_mfma_f32_16x16x32_bf16 v[100:103], v[136:139], v[24:27], v[100:103]
	v_mfma_f32_16x16x32_bf16 v[100:103], v[140:143], v[28:31], v[100:103]
	ds_read_b128 v[128:131], v225 offset:17152
	ds_read_b128 v[132:135], v225 offset:17216
	ds_read_b128 v[136:139], v225 offset:17280
	ds_read_b128 v[140:143], v225 offset:17344
	s_waitcnt lgkmcnt(4)
	v_mfma_f32_16x16x32_bf16 v[104:107], v[112:115], v[0:3], 0
	v_mfma_f32_16x16x32_bf16 v[104:107], v[116:119], v[4:7], v[104:107]
	v_mfma_f32_16x16x32_bf16 v[104:107], v[120:123], v[8:11], v[104:107]
	v_mfma_f32_16x16x32_bf16 v[104:107], v[124:127], v[12:15], v[104:107]
	ds_read_b128 v[112:115], v225 offset:25344
	ds_read_b128 v[116:119], v225 offset:25408
	ds_read_b128 v[120:123], v225 offset:25472
	ds_read_b128 v[124:127], v225 offset:25536
	s_waitcnt lgkmcnt(4)
	v_mfma_f32_16x16x32_bf16 v[104:107], v[128:131], v[16:19], v[104:107]
	v_mfma_f32_16x16x32_bf16 v[104:107], v[132:135], v[20:23], v[104:107]
	v_mfma_f32_16x16x32_bf16 v[104:107], v[136:139], v[24:27], v[104:107]
	v_mfma_f32_16x16x32_bf16 v[104:107], v[140:143], v[28:31], v[104:107]
	ds_read_b128 v[128:131], v225 offset:25600
	ds_read_b128 v[132:135], v225 offset:25664
	ds_read_b128 v[136:139], v225 offset:25728
	ds_read_b128 v[140:143], v225 offset:25792
	s_waitcnt lgkmcnt(4)
	v_mfma_f32_16x16x32_bf16 v[108:111], v[112:115], v[0:3], 0
	v_mfma_f32_16x16x32_bf16 v[108:111], v[116:119], v[4:7], v[108:111]
	v_mfma_f32_16x16x32_bf16 v[108:111], v[120:123], v[8:11], v[108:111]
	v_mfma_f32_16x16x32_bf16 v[108:111], v[124:127], v[12:15], v[108:111]
	s_waitcnt lgkmcnt(0)
; DEVI unsigned pack2(float a, float b) { return (unsigned)f2bf(a) | ((unsigned)f2bf(b) << 16); }
; DEVI float fexp2(float x) { return __builtin_amdgcn_exp2f(x); }
; template <int DH, int NQ, int LDK, class MaskF>
; DEVI void attn_qk(const u16* sK, const bf16x8 (&qf)[NQ][DH / 32], f32x4 (&o)[NQ][DH / 16], float (&m)[NQ], float (&l)[NQ],
;                   float c2, int lane, MaskF valid, bf16x8 (&pb)[NQ][2]) {
;     ...
; #pragma unroll
;   for (int qt = 0; qt < NQ; ++qt) {
;     float mx = -1e30f;
; #pragma unroll
;     for (int kt = 0; kt < 4; ++kt)
; #pragma unroll
;       for (int r = 0; r < 4; ++r) {
;         const bool v = valid(qt, 16 * kt + 4 * quad + r);
;         const float sv = v ? s[qt][kt][r] : -1e30f;
;         s[qt][kt][r] = sv;
;         mx = fmaxf(mx, sv);
;       }
;     mx = fmaxf(mx, __shfl_xor(mx, 16));
;     mx = fmaxf(mx, __shfl_xor(mx, 32));
;     const float mn = fmaxf(m[qt], mx);
;     const float alpha = fexp2((m[qt] - mn) * c2);
;     m[qt] = mn;
;     const float mc = fmaxf(mn, -1e20f) * c2;
;     float ps = 0.f;
; #pragma unroll
;     for (int kt = 0; kt < 4; ++kt)
; #pragma unroll
;       for (int r = 0; r < 4; ++r) {
;         const float pv = fexp2(__builtin_fmaf(s[qt][kt][r], c2, -mc));
;         ps += pv;
;         s[qt][kt][r] = pv;
;       }
;     l[qt] = l[qt] * alpha + ps;
; #pragma unroll
;     for (int dt = 0; dt < DH / 16; ++dt) o[qt][dt] *= alpha;
; #pragma unroll
;     for (int kk = 0; kk < 2; ++kk) {
;       union { bf16x8 v; unsigned u[4]; } cv;
;       cv.u[0] = pack2(s[qt][2 * kk][0], s[qt][2 * kk][1]);
;       cv.u[1] = pack2(s[qt][2 * kk][2], s[qt][2 * kk][3]);
;       cv.u[2] = pack2(s[qt][2 * kk + 1][0], s[qt][2 * kk + 1][1]);
;       cv.u[3] = pack2(s[qt][2 * kk + 1][2], s[qt][2 * kk + 1][3]);
;       pb[qt][kk] = cv.v;
;     }
;   }
	v_mfma_f32_16x16x32_bf16 v[108:111], v[128:131], v[16:19], v[108:111]
	v_mfma_f32_16x16x32_bf16 v[108:111], v[132:135], v[20:23], v[108:111]
	v_mfma_f32_16x16x32_bf16 v[108:111], v[136:139], v[24:27], v[108:111]
	v_mfma_f32_16x16x32_bf16 v[108:111], v[140:143], v[28:31], v[108:111]
	s_nop 7
	v_max3_f32 v235, v96, v97, v98
	v_max3_f32 v235, v235, v99, v100
	v_max3_f32 v235, v235, v101, v102
	v_max3_f32 v235, v235, v103, v104
	v_max3_f32 v235, v235, v105, v106
	v_max3_f32 v235, v235, v107, v108
	v_max3_f32 v235, v235, v109, v110
	v_max_f32_e32 v235, v111, v235
	ds_bpermute_b32 v236, v228, v235
	s_waitcnt lgkmcnt(0)
	v_max_f32_e32 v235, v236, v235
	v_mov_b32_e32 v236, v235
	v_mov_b32_e32 v237, v235
	s_nop 1
	v_permlane32_swap_b32_e32 v236, v237
	v_max_f32_e32 v235, v236, v237
	v_max_f32_e32 v238, v229, v235
	v_sub_f32_e32 v239, v229, v238
	v_mul_f32_e32 v239, 0x3db8aa3b, v239
	v_exp_f32_e32 v239, v239
	v_mov_b32_e32 v229, v238
	v_mul_f32_e32 v240, 0xbdb8aa3b, v238
	v_fma_f32 v96, v96, v242, v240
	v_exp_f32_e32 v96, v96
	v_fma_f32 v97, v97, v242, v240
	v_exp_f32_e32 v97, v97
	v_fma_f32 v98, v98, v242, v240
	v_exp_f32_e32 v98, v98
	v_fma_f32 v99, v99, v242, v240
	v_exp_f32_e32 v99, v99
	v_fma_f32 v100, v100, v242, v240
	v_exp_f32_e32 v100, v100
	v_fma_f32 v101, v101, v242, v240
	v_exp_f32_e32 v101, v101
	v_fma_f32 v102, v102, v242, v240
	v_exp_f32_e32 v102, v102
	v_fma_f32 v103, v103, v242, v240
	v_exp_f32_e32 v103, v103
	v_fma_f32 v104, v104, v242, v240
	v_exp_f32_e32 v104, v104
	v_fma_f32 v105, v105, v242, v240
	v_exp_f32_e32 v105, v105
	v_fma_f32 v106, v106, v242, v240
	v_exp_f32_e32 v106, v106
	v_fma_f32 v107, v107, v242, v240
	v_exp_f32_e32 v107, v107
	v_fma_f32 v108, v108, v242, v240
	v_exp_f32_e32 v108, v108
	v_fma_f32 v109, v109, v242, v240
	v_exp_f32_e32 v109, v109
	v_fma_f32 v110, v110, v242, v240
	v_exp_f32_e32 v110, v110
	v_fma_f32 v111, v111, v242, v240
	v_exp_f32_e32 v111, v111
	s_nop 0
	v_add_f32_e32 v241, v96, v97
	v_add_f32_e32 v241, v98, v241
	v_add_f32_e32 v241, v99, v241
	v_add_f32_e32 v241, v100, v241
	v_add_f32_e32 v241, v101, v241
	v_add_f32_e32 v241, v102, v241
	v_add_f32_e32 v241, v103, v241
	v_add_f32_e32 v241, v104, v241
	v_add_f32_e32 v241, v105, v241
	v_add_f32_e32 v241, v106, v241
	v_add_f32_e32 v241, v107, v241
	v_add_f32_e32 v241, v108, v241
	v_add_f32_e32 v241, v109, v241
	v_add_f32_e32 v241, v110, v241
	v_add_f32_e32 v241, v111, v241
	v_fma_f32 v230, v230, v239, v241
	v_mul_f32_e32 v32, v239, v32
	v_mul_f32_e32 v33, v239, v33
	v_mul_f32_e32 v34, v239, v34
	v_mul_f32_e32 v35, v239, v35
	v_mul_f32_e32 v36, v239, v36
	v_mul_f32_e32 v37, v239, v37
	v_mul_f32_e32 v38, v239, v38
	v_mul_f32_e32 v39, v239, v39
	v_mul_f32_e32 v40, v239, v40
	v_mul_f32_e32 v41, v239, v41
	v_mul_f32_e32 v42, v239, v42
	v_mul_f32_e32 v43, v239, v43
	v_mul_f32_e32 v44, v239, v44
	v_mul_f32_e32 v45, v239, v45
	v_mul_f32_e32 v46, v239, v46
	v_mul_f32_e32 v47, v239, v47
	v_mul_f32_e32 v48, v239, v48
	v_mul_f32_e32 v49, v239, v49
	v_mul_f32_e32 v50, v239, v50
	v_mul_f32_e32 v51, v239, v51
	v_mul_f32_e32 v52, v239, v52
	v_mul_f32_e32 v53, v239, v53
	v_mul_f32_e32 v54, v239, v54
	v_mul_f32_e32 v55, v239, v55
	v_mul_f32_e32 v56, v239, v56
	v_mul_f32_e32 v57, v239, v57
	v_mul_f32_e32 v58, v239, v58
	v_mul_f32_e32 v59, v239, v59
	v_mul_f32_e32 v60, v239, v60
	v_mul_f32_e32 v61, v239, v61
	v_mul_f32_e32 v62, v239, v62
	v_mul_f32_e32 v63, v239, v63
	v_mul_f32_e32 v64, v239, v64
	v_mul_f32_e32 v65, v239, v65
	v_mul_f32_e32 v66, v239, v66
	v_mul_f32_e32 v67, v239, v67
	v_mul_f32_e32 v68, v239, v68
	v_mul_f32_e32 v69, v239, v69
	v_mul_f32_e32 v70, v239, v70
	v_mul_f32_e32 v71, v239, v71
	v_mul_f32_e32 v72, v239, v72
	v_mul_f32_e32 v73, v239, v73
	v_mul_f32_e32 v74, v239, v74
	v_mul_f32_e32 v75, v239, v75
	v_mul_f32_e32 v76, v239, v76
	v_mul_f32_e32 v77, v239, v77
	v_mul_f32_e32 v78, v239, v78
	v_mul_f32_e32 v79, v239, v79
	v_mul_f32_e32 v80, v239, v80
	v_mul_f32_e32 v81, v239, v81
	v_mul_f32_e32 v82, v239, v82
	v_mul_f32_e32 v83, v239, v83
	v_mul_f32_e32 v84, v239, v84
	v_mul_f32_e32 v85, v239, v85
	v_mul_f32_e32 v86, v239, v86
	v_mul_f32_e32 v87, v239, v87
	v_mul_f32_e32 v88, v239, v88
	v_mul_f32_e32 v89, v239, v89
	v_mul_f32_e32 v90, v239, v90
	v_mul_f32_e32 v91, v239, v91
	v_mul_f32_e32 v92, v239, v92
	v_mul_f32_e32 v93, v239, v93
	v_mul_f32_e32 v94, v239, v94
	v_mul_f32_e32 v95, v239, v95
	v_cvt_pk_bf16_f32 v212, v96, v97
	v_cvt_pk_bf16_f32 v213, v98, v99
	v_cvt_pk_bf16_f32 v214, v100, v101
	v_cvt_pk_bf16_f32 v215, v102, v103
	v_cvt_pk_bf16_f32 v216, v104, v105
	v_cvt_pk_bf16_f32 v217, v106, v107
	v_cvt_pk_bf16_f32 v218, v108, v109
	v_cvt_pk_bf16_f32 v219, v110, v111
	s_waitcnt vmcnt(8)
	ds_write_b128 v224, v[176:179]
	ds_write_b128 v224, v[180:183] offset:4608
	ds_write_b128 v224, v[184:187] offset:9216
	ds_write_b128 v224, v[188:191] offset:13824
	ds_write_b128 v224, v[192:195] offset:18432
	ds_write_b128 v224, v[196:199] offset:23040
	ds_write_b128 v224, v[200:203] offset:27648
	ds_write_b128 v224, v[204:207] offset:32256
	s_waitcnt lgkmcnt(0)
	s_barrier
; DEVI f32x4 mfma16(bf16x8 a, bf16x8 b, f32x4 c) { return __builtin_amdgcn_mfma_f32_16x16x32_bf16(a, b, c, 0, 0, 0); }
; #define STOREK_() SK1_(0) SK1_(1) SK1_(2) SK1_(3) SK1_(4) SK1_(5) SK1_(6) SK1_(7)
; #define LOADV_(kbx) LV1_(0, kbx) LV1_(1, kbx) LV1_(2, kbx) LV1_(3, kbx) LV1_(4, kbx) LV1_(5, kbx) LV1_(6, kbx) LV1_(7, kbx)
; template <int DH, int NQ, int LDV>
; DEVI void attn_pv(const u16* sVt, const bf16x8 (&pb)[NQ][2], f32x4 (&o)[NQ][DH / 16], int lane) {
;   const int col = lane & 15, quad = lane >> 4;
;   __builtin_amdgcn_s_setprio(1);
; #pragma unroll
;   for (int dt = 0; dt < DH / 16; ++dt) {
; #pragma unroll
;     for (int kk = 0; kk < 2; ++kk) {
;       union { bf16x8 v; uint2 h[2]; } cv;
;       cv.h[0] = *(const uint2*)(sVt + (16 * dt + col) * LDV + 32 * kk + 4 * quad);
;       cv.h[1] = *(const uint2*)(sVt + (16 * dt + col) * LDV + 32 * kk + 16 + 4 * quad);
; #pragma unroll
;       for (int qt = 0; qt < NQ; ++qt) o[qt][dt] = mfma16(cv.v, pb[qt][kk], o[qt][dt]);
;     }
;   }
;   __builtin_amdgcn_s_setprio(0);
; }
; DEVI void phase_memattn(const Params& p, unsigned char* smem) {
;     ...
;       if (kb < 3) {
;         STOREK_()
;         LOADV_(kb + 1)
	s_lshl_b32 s16, s10, 2
	s_add_u32 s16, s16, s11
	s_lshl_b32 s16, s16, 17
	s_add_u32 s16, s16, 384
	v_add_u32_e32 v231, s16, v222
	global_load_dwordx4 v[176:179], v231, s[4:5]
	s_add_u32 s16, s16, 0x4000
	v_add_u32_e32 v232, s16, v222
	global_load_dwordx4 v[180:183], v232, s[4:5]
	s_add_u32 s16, s16, 0x4000
	v_add_u32_e32 v233, s16, v222
	global_load_dwordx4 v[184:187], v233, s[4:5]
	s_add_u32 s16, s16, 0x4000
	v_add_u32_e32 v234, s16, v222
	global_load_dwordx4 v[188:191], v234, s[4:5]
	s_add_u32 s16, s16, 0x4000
	v_add_u32_e32 v231, s16, v222
	global_load_dwordx4 v[192:195], v231, s[4:5]
	s_add_u32 s16, s16, 0x4000
	v_add_u32_e32 v232, s16, v222
	global_load_dwordx4 v[196:199], v232, s[4:5]
	s_add_u32 s16, s16, 0x4000
	v_add_u32_e32 v233, s16, v222
	global_load_dwordx4 v[200:203], v233, s[4:5]
	s_add_u32 s16, s16, 0x4000
	v_add_u32_e32 v234, s16, v222
	global_load_dwordx4 v[204:207], v234, s[4:5]
	ds_read_b64 v[112:113], v226 offset:0
	ds_read_b64 v[114:115], v226 offset:32
	ds_read_b64 v[116:117], v226 offset:64
	ds_read_b64 v[118:119], v226 offset:96
	ds_read_b64 v[120:121], v226 offset:2304
	ds_read_b64 v[122:123], v226 offset:2336
	ds_read_b64 v[124:125], v226 offset:2368
	ds_read_b64 v[126:127], v226 offset:2400
	ds_read_b64 v[128:129], v226 offset:4608
	ds_read_b64 v[130:131], v226 offset:4640
	ds_read_b64 v[132:133], v226 offset:4672
	ds_read_b64 v[134:135], v226 offset:4704
	ds_read_b64 v[136:137], v226 offset:6912
	ds_read_b64 v[138:139], v226 offset:6944
	ds_read_b64 v[140:141], v226 offset:6976
	ds_read_b64 v[142:143], v226 offset:7008
	s_waitcnt lgkmcnt(14)
	v_mfma_f32_16x16x32_bf16 v[32:35], v[112:115], v[212:215], v[32:35]
	ds_read_b64 v[112:113], v226 offset:9216
	ds_read_b64 v[114:115], v226 offset:9248
	s_waitcnt lgkmcnt(14)
	v_mfma_f32_16x16x32_bf16 v[32:35], v[116:119], v[216:219], v[32:35]
	ds_read_b64 v[116:117], v226 offset:9280
	ds_read_b64 v[118:119], v226 offset:9312
	s_waitcnt lgkmcnt(14)
	v_mfma_f32_16x16x32_bf16 v[36:39], v[120:123], v[212:215], v[36:39]
	ds_read_b64 v[120:121], v226 offset:11520
	ds_read_b64 v[122:123], v226 offset:11552
	s_waitcnt lgkmcnt(14)
	v_mfma_f32_16x16x32_bf16 v[36:39], v[124:127], v[216:219], v[36:39]
	ds_read_b64 v[124:125], v226 offset:11584
	ds_read_b64 v[126:127], v226 offset:11616
	s_waitcnt lgkmcnt(14)
	v_mfma_f32_16x16x32_bf16 v[40:43], v[128:131], v[212:215], v[40:43]
	ds_read_b64 v[128:129], v226 offset:13824
	ds_read_b64 v[130:131], v226 offset:13856
	s_waitcnt lgkmcnt(14)
	v_mfma_f32_16x16x32_bf16 v[40:43], v[132:135], v[216:219], v[40:43]
	ds_read_b64 v[132:133], v226 offset:13888
	ds_read_b64 v[134:135], v226 offset:13920
	s_waitcnt lgkmcnt(14)
	v_mfma_f32_16x16x32_bf16 v[44:47], v[136:139], v[212:215], v[44:47]
	ds_read_b64 v[136:137], v226 offset:16128
	ds_read_b64 v[138:139], v226 offset:16160
	s_waitcnt lgkmcnt(14)
	v_mfma_f32_16x16x32_bf16 v[44:47], v[140:143], v[216:219], v[44:47]
	ds_read_b64 v[140:141], v226 offset:16192
	ds_read_b64 v[142:143], v226 offset:16224
	s_waitcnt lgkmcnt(14)
	v_mfma_f32_16x16x32_bf16 v[48:51], v[112:115], v[212:215], v[48:51]
	ds_read_b64 v[112:113], v226 offset:18432
	ds_read_b64 v[114:115], v226 offset:18464
	s_waitcnt lgkmcnt(14)
	v_mfma_f32_16x16x32_bf16 v[48:51], v[116:119], v[216:219], v[48:51]
	ds_read_b64 v[116:117], v226 offset:18496
	ds_read_b64 v[118:119], v226 offset:18528
	s_waitcnt lgkmcnt(14)
	v_mfma_f32_16x16x32_bf16 v[52:55], v[120:123], v[212:215], v[52:55]
	ds_read_b64 v[120:121], v226 offset:20736
	ds_read_b64 v[122:123], v226 offset:20768
	s_waitcnt lgkmcnt(14)
	v_mfma_f32_16x16x32_bf16 v[52:55], v[124:127], v[216:219], v[52:55]
	ds_read_b64 v[124:125], v226 offset:20800
	ds_read_b64 v[126:127], v226 offset:20832
	s_waitcnt lgkmcnt(14)
	v_mfma_f32_16x16x32_bf16 v[56:59], v[128:131], v[212:215], v[56:59]
	ds_read_b64 v[128:129], v226 offset:23040
	ds_read_b64 v[130:131], v226 offset:23072
	s_waitcnt lgkmcnt(14)
	v_mfma_f32_16x16x32_bf16 v[56:59], v[132:135], v[216:219], v[56:59]
	ds_read_b64 v[132:133], v226 offset:23104
	ds_read_b64 v[134:135], v226 offset:23136
	s_waitcnt lgkmcnt(14)
	v_mfma_f32_16x16x32_bf16 v[60:63], v[136:139], v[212:215], v[60:63]
	ds_read_b64 v[136:137], v226 offset:25344
	ds_read_b64 v[138:139], v226 offset:25376
	s_waitcnt lgkmcnt(14)
	v_mfma_f32_16x16x32_bf16 v[60:63], v[140:143], v[216:219], v[60:63]
	ds_read_b64 v[140:141], v226 offset:25408
	ds_read_b64 v[142:143], v226 offset:25440
	s_waitcnt lgkmcnt(14)
	v_mfma_f32_16x16x32_bf16 v[64:67], v[112:115], v[212:215], v[64:67]
	ds_read_b64 v[112:113], v226 offset:27648
	ds_read_b64 v[114:115], v226 offset:27680
	s_waitcnt lgkmcnt(14)
	v_mfma_f32_16x16x32_bf16 v[64:67], v[116:119], v[216:219], v[64:67]
	ds_read_b64 v[116:117], v226 offset:27712
	ds_read_b64 v[118:119], v226 offset:27744
	s_waitcnt lgkmcnt(14)
	v_mfma_f32_16x16x32_bf16 v[68:71], v[120:123], v[212:215], v[68:71]
	ds_read_b64 v[120:121], v226 offset:29952
	ds_read_b64 v[122:123], v226 offset:29984
	s_waitcnt lgkmcnt(14)
	v_mfma_f32_16x16x32_bf16 v[68:71], v[124:127], v[216:219], v[68:71]
	ds_read_b64 v[124:125], v226 offset:30016
	ds_read_b64 v[126:127], v226 offset:30048
	s_waitcnt lgkmcnt(14)
	v_mfma_f32_16x16x32_bf16 v[72:75], v[128:131], v[212:215], v[72:75]
	ds_read_b64 v[128:129], v226 offset:32256
	ds_read_b64 v[130:131], v226 offset:32288
	s_waitcnt lgkmcnt(14)
	v_mfma_f32_16x16x32_bf16 v[72:75], v[132:135], v[216:219], v[72:75]
	ds_read_b64 v[132:133], v226 offset:32320
	ds_read_b64 v[134:135], v226 offset:32352
	s_waitcnt lgkmcnt(14)
	v_mfma_f32_16x16x32_bf16 v[76:79], v[136:139], v[212:215], v[76:79]
	ds_read_b64 v[136:137], v226 offset:34560
	ds_read_b64 v[138:139], v226 offset:34592
	s_waitcnt lgkmcnt(14)
	v_mfma_f32_16x16x32_bf16 v[76:79], v[140:143], v[216:219], v[76:79]
	ds_read_b64 v[140:141], v226 offset:34624
	ds_read_b64 v[142:143], v226 offset:34656
	s_waitcnt lgkmcnt(14)
	v_mfma_f32_16x16x32_bf16 v[80:83], v[112:115], v[212:215], v[80:83]
	s_waitcnt lgkmcnt(12)
	v_mfma_f32_16x16x32_bf16 v[80:83], v[116:119], v[216:219], v[80:83]
	s_waitcnt lgkmcnt(10)
	v_mfma_f32_16x16x32_bf16 v[84:87], v[120:123], v[212:215], v[84:87]
	s_waitcnt lgkmcnt(8)
	v_mfma_f32_16x16x32_bf16 v[84:87], v[124:127], v[216:219], v[84:87]
	s_waitcnt lgkmcnt(6)
	v_mfma_f32_16x16x32_bf16 v[88:91], v[128:131], v[212:215], v[88:91]
	s_waitcnt lgkmcnt(4)
	v_mfma_f32_16x16x32_bf16 v[88:91], v[132:135], v[216:219], v[88:91]
	s_waitcnt lgkmcnt(2)
	v_mfma_f32_16x16x32_bf16 v[92:95], v[136:139], v[212:215], v[92:95]
	s_waitcnt lgkmcnt(0)
	v_mfma_f32_16x16x32_bf16 v[92:95], v[140:143], v[216:219], v[92:95]
	s_waitcnt vmcnt(8)
	ds_write_b128 v223, v[144:147]
	ds_write_b128 v223, v[148:151] offset:4224
	ds_write_b128 v223, v[152:155] offset:8448
	ds_write_b128 v223, v[156:159] offset:12672
	ds_write_b128 v223, v[160:163] offset:16896
	ds_write_b128 v223, v[164:167] offset:21120
	ds_write_b128 v223, v[168:171] offset:25344
	ds_write_b128 v223, v[172:175] offset:29568
	s_waitcnt lgkmcnt(0)
	s_barrier
; DEVI f32x4 mfma16(bf16x8 a, bf16x8 b, f32x4 c) { return __builtin_amdgcn_mfma_f32_16x16x32_bf16(a, b, c, 0, 0, 0); }
; DEVI float fexp2(float x) { return __builtin_amdgcn_exp2f(x); }
; template <int DH, int NQ, int LDK, class MaskF>
; DEVI void attn_qk(const u16* sK, const bf16x8 (&qf)[NQ][DH / 32], f32x4 (&o)[NQ][DH / 16], float (&m)[NQ], float (&l)[NQ],
;                   float c2, int lane, MaskF valid, bf16x8 (&pb)[NQ][2]) {
;     ...
;   for (int kt = 0; kt < 4; ++kt) {
; #pragma unroll
;     for (int qt = 0; qt < NQ; ++qt) s[qt][kt] = f32x4{0.f, 0.f, 0.f, 0.f};
; #pragma unroll
;     for (int ks = 0; ks < DH / 32; ++ks) {
;       const bf16x8 kf = *(const bf16x8*)(sK + (16 * kt + col) * LDK + 32 * ks + 8 * quad);
; #pragma unroll
;       for (int qt = 0; qt < NQ; ++qt) s[qt][kt] = mfma16(kf, qf[qt][ks], s[qt][kt]);
;     }
;   }
;   __builtin_amdgcn_s_setprio(0);
; #pragma unroll
;   for (int qt = 0; qt < NQ; ++qt) {
;     float mx = -1e30f;
; #pragma unroll
;     for (int kt = 0; kt < 4; ++kt)
; #pragma unroll
;       for (int r = 0; r < 4; ++r) {
;         const bool v = valid(qt, 16 * kt + 4 * quad + r);
;         const float sv = v ? s[qt][kt][r] : -1e30f;
;         s[qt][kt][r] = sv;
;         mx = fmaxf(mx, sv);
;       }
;     mx = fmaxf(mx, __shfl_xor(mx, 16));
;     mx = fmaxf(mx, __shfl_xor(mx, 32));
;     const float mn = fmaxf(m[qt], mx);
;     const float alpha = fexp2((m[qt] - mn) * c2);
;     m[qt] = mn;
;     const float mc = fmaxf(mn, -1e20f) * c2;
;     float ps = 0.f;
; #pragma unroll
;     for (int kt = 0; kt < 4; ++kt)
; #pragma unroll
;       for (int r = 0; r < 4; ++r) {
;         const float pv = fexp2(__builtin_fmaf(s[qt][kt][r], c2, -mc));
;         ps += pv;
;         s[qt][kt][r] = pv;
;       }
;     l[qt] = l[qt] * alpha + ps;
	ds_read_b128 v[112:115], v225
	ds_read_b128 v[116:119], v225 offset:64
	ds_read_b128 v[120:123], v225 offset:128
	ds_read_b128 v[124:127], v225 offset:192
	ds_read_b128 v[128:131], v225 offset:256
	ds_read_b128 v[132:135], v225 offset:320
	ds_read_b128 v[136:139], v225 offset:384
	ds_read_b128 v[140:143], v225 offset:448
	s_waitcnt lgkmcnt(4)
	v_mfma_f32_16x16x32_bf16 v[96:99], v[112:115], v[0:3], 0
	v_mfma_f32_16x16x32_bf16 v[96:99], v[116:119], v[4:7], v[96:99]
	v_mfma_f32_16x16x32_bf16 v[96:99], v[120:123], v[8:11], v[96:99]
	v_mfma_f32_16x16x32_bf16 v[96:99], v[124:127], v[12:15], v[96:99]
	ds_read_b128 v[112:115], v225 offset:8448
	ds_read_b128 v[116:119], v225 offset:8512
	ds_read_b128 v[120:123], v225 offset:8576
	ds_read_b128 v[124:127], v225 offset:8640
	s_waitcnt lgkmcnt(4)
	v_mfma_f32_16x16x32_bf16 v[96:99], v[128:131], v[16:19], v[96:99]
	v_mfma_f32_16x16x32_bf16 v[96:99], v[132:135], v[20:23], v[96:99]
	v_mfma_f32_16x16x32_bf16 v[96:99], v[136:139], v[24:27], v[96:99]
	v_mfma_f32_16x16x32_bf16 v[96:99], v[140:143], v[28:31], v[96:99]
	ds_read_b128 v[128:131], v225 offset:8704
	ds_read_b128 v[132:135], v225 offset:8768
	ds_read_b128 v[136:139], v225 offset:8832
	ds_read_b128 v[140:143], v225 offset:8896
	s_waitcnt lgkmcnt(4)
	v_mfma_f32_16x16x32_bf16 v[100:103], v[112:115], v[0:3], 0
	v_mfma_f32_16x16x32_bf16 v[100:103], v[116:119], v[4:7], v[100:103]
	v_mfma_f32_16x16x32_bf16 v[100:103], v[120:123], v[8:11], v[100:103]
	v_mfma_f32_16x16x32_bf16 v[100:103], v[124:127], v[12:15], v[100:103]
	ds_read_b128 v[112:115], v225 offset:16896
	ds_read_b128 v[116:119], v225 offset:16960
	ds_read_b128 v[120:123], v225 offset:17024
	ds_read_b128 v[124:127], v225 offset:17088
	s_waitcnt lgkmcnt(4)
	v_mfma_f32_16x16x32_bf16 v[100:103], v[128:131], v[16:19], v[100:103]
	v_mfma_f32_16x16x32_bf16 v[100:103], v[132:135], v[20:23], v[100:103]
	v_mfma_f32_16x16x32_bf16 v[100:103], v[136:139], v[24:27], v[100:103]
	v_mfma_f32_16x16x32_bf16 v[100:103], v[140:143], v[28:31], v[100:103]
	ds_read_b128 v[128:131], v225 offset:17152
	ds_read_b128 v[132:135], v225 offset:17216
	ds_read_b128 v[136:139], v225 offset:17280
	ds_read_b128 v[140:143], v225 offset:17344
	s_waitcnt lgkmcnt(4)
	v_mfma_f32_16x16x32_bf16 v[104:107], v[112:115], v[0:3], 0
	v_mfma_f32_16x16x32_bf16 v[104:107], v[116:119], v[4:7], v[104:107]
	v_mfma_f32_16x16x32_bf16 v[104:107], v[120:123], v[8:11], v[104:107]
	v_mfma_f32_16x16x32_bf16 v[104:107], v[124:127], v[12:15], v[104:107]
	ds_read_b128 v[112:115], v225 offset:25344
	ds_read_b128 v[116:119], v225 offset:25408
	ds_read_b128 v[120:123], v225 offset:25472
	ds_read_b128 v[124:127], v225 offset:25536
	s_waitcnt lgkmcnt(4)
	v_mfma_f32_16x16x32_bf16 v[104:107], v[128:131], v[16:19], v[104:107]
	v_mfma_f32_16x16x32_bf16 v[104:107], v[132:135], v[20:23], v[104:107]
	v_mfma_f32_16x16x32_bf16 v[104:107], v[136:139], v[24:27], v[104:107]
	v_mfma_f32_16x16x32_bf16 v[104:107], v[140:143], v[28:31], v[104:107]
	ds_read_b128 v[128:131], v225 offset:25600
	ds_read_b128 v[132:135], v225 offset:25664
	ds_read_b128 v[136:139], v225 offset:25728
	ds_read_b128 v[140:143], v225 offset:25792
	s_waitcnt lgkmcnt(4)
	v_mfma_f32_16x16x32_bf16 v[108:111], v[112:115], v[0:3], 0
	v_mfma_f32_16x16x32_bf16 v[108:111], v[116:119], v[4:7], v[108:111]
	v_mfma_f32_16x16x32_bf16 v[108:111], v[120:123], v[8:11], v[108:111]
	v_mfma_f32_16x16x32_bf16 v[108:111], v[124:127], v[12:15], v[108:111]
	s_waitcnt lgkmcnt(0)
	v_mfma_f32_16x16x32_bf16 v[108:111], v[128:131], v[16:19], v[108:111]
	v_mfma_f32_16x16x32_bf16 v[108:111], v[132:135], v[20:23], v[108:111]
	v_mfma_f32_16x16x32_bf16 v[108:111], v[136:139], v[24:27], v[108:111]
	v_mfma_f32_16x16x32_bf16 v[108:111], v[140:143], v[28:31], v[108:111]
	s_nop 7
	v_max3_f32 v235, v96, v97, v98
	v_max3_f32 v235, v235, v99, v100
	v_max3_f32 v235, v235, v101, v102
	v_max3_f32 v235, v235, v103, v104
	v_max3_f32 v235, v235, v105, v106
	v_max3_f32 v235, v235, v107, v108
	v_max3_f32 v235, v235, v109, v110
	v_max_f32_e32 v235, v111, v235
	ds_bpermute_b32 v236, v228, v235
	s_waitcnt lgkmcnt(0)
	v_max_f32_e32 v235, v236, v235
	v_mov_b32_e32 v236, v235
	v_mov_b32_e32 v237, v235
	s_nop 1
	v_permlane32_swap_b32_e32 v236, v237
	v_max_f32_e32 v235, v236, v237
	v_max_f32_e32 v238, v229, v235
	v_sub_f32_e32 v239, v229, v238
	v_mul_f32_e32 v239, 0x3db8aa3b, v239
	v_exp_f32_e32 v239, v239
	v_mov_b32_e32 v229, v238
	v_mul_f32_e32 v240, 0xbdb8aa3b, v238
	v_fma_f32 v96, v96, v242, v240
	v_exp_f32_e32 v96, v96
	v_fma_f32 v97, v97, v242, v240
	v_exp_f32_e32 v97, v97
	v_fma_f32 v98, v98, v242, v240
	v_exp_f32_e32 v98, v98
	v_fma_f32 v99, v99, v242, v240
	v_exp_f32_e32 v99, v99
	v_fma_f32 v100, v100, v242, v240
	v_exp_f32_e32 v100, v100
	v_fma_f32 v101, v101, v242, v240
	v_exp_f32_e32 v101, v101
	v_fma_f32 v102, v102, v242, v240
	v_exp_f32_e32 v102, v102
	v_fma_f32 v103, v103, v242, v240
	v_exp_f32_e32 v103, v103
	v_fma_f32 v104, v104, v242, v240
	v_exp_f32_e32 v104, v104
	v_fma_f32 v105, v105, v242, v240
	v_exp_f32_e32 v105, v105
	v_fma_f32 v106, v106, v242, v240
	v_exp_f32_e32 v106, v106
	v_fma_f32 v107, v107, v242, v240
	v_exp_f32_e32 v107, v107
	v_fma_f32 v108, v108, v242, v240
	v_exp_f32_e32 v108, v108
	v_fma_f32 v109, v109, v242, v240
	v_exp_f32_e32 v109, v109
	v_fma_f32 v110, v110, v242, v240
	v_exp_f32_e32 v110, v110
	v_fma_f32 v111, v111, v242, v240
	v_exp_f32_e32 v111, v111
	s_nop 0
	v_add_f32_e32 v241, v96, v97
	v_add_f32_e32 v241, v98, v241
	v_add_f32_e32 v241, v99, v241
	v_add_f32_e32 v241, v100, v241
	v_add_f32_e32 v241, v101, v241
	v_add_f32_e32 v241, v102, v241
	v_add_f32_e32 v241, v103, v241
	v_add_f32_e32 v241, v104, v241
; DEVI unsigned pack2(float a, float b) { return (unsigned)f2bf(a) | ((unsigned)f2bf(b) << 16); }
; DEVI f32x4 mfma16(bf16x8 a, bf16x8 b, f32x4 c) { return __builtin_amdgcn_mfma_f32_16x16x32_bf16(a, b, c, 0, 0, 0); }
; template <int DH, int NQ, int LDK, class MaskF>
; DEVI void attn_qk(const u16* sK, const bf16x8 (&qf)[NQ][DH / 32], f32x4 (&o)[NQ][DH / 16], float (&m)[NQ], float (&l)[NQ],
;                   float c2, int lane, MaskF valid, bf16x8 (&pb)[NQ][2]) {
;     ...
;     l[qt] = l[qt] * alpha + ps;
; #pragma unroll
;     for (int dt = 0; dt < DH / 16; ++dt) o[qt][dt] *= alpha;
; #pragma unroll
;     for (int kk = 0; kk < 2; ++kk) {
;       union { bf16x8 v; unsigned u[4]; } cv;
;       cv.u[0] = pack2(s[qt][2 * kk][0], s[qt][2 * kk][1]);
;       cv.u[1] = pack2(s[qt][2 * kk][2], s[qt][2 * kk][3]);
;       cv.u[2] = pack2(s[qt][2 * kk + 1][0], s[qt][2 * kk + 1][1]);
;       cv.u[3] = pack2(s[qt][2 * kk + 1][2], s[qt][2 * kk + 1][3]);
;       pb[qt][kk] = cv.v;
;     }
;   }
; }
; template <int DH, int NQ, int LDV>
; DEVI void attn_pv(const u16* sVt, const bf16x8 (&pb)[NQ][2], f32x4 (&o)[NQ][DH / 16], int lane) {
;   const int col = lane & 15, quad = lane >> 4;
;   __builtin_amdgcn_s_setprio(1);
; #pragma unroll
;   for (int dt = 0; dt < DH / 16; ++dt) {
; #pragma unroll
;     for (int kk = 0; kk < 2; ++kk) {
;       union { bf16x8 v; uint2 h[2]; } cv;
;       cv.h[0] = *(const uint2*)(sVt + (16 * dt + col) * LDV + 32 * kk + 4 * quad);
;       cv.h[1] = *(const uint2*)(sVt + (16 * dt + col) * LDV + 32 * kk + 16 + 4 * quad);
; #pragma unroll
;       for (int qt = 0; qt < NQ; ++qt) o[qt][dt] = mfma16(cv.v, pb[qt][kk], o[qt][dt]);
;     }
;   }
;   __builtin_amdgcn_s_setprio(0);
; }
	v_add_f32_e32 v241, v105, v241
	v_add_f32_e32 v241, v106, v241
	v_add_f32_e32 v241, v107, v241
	v_add_f32_e32 v241, v108, v241
	v_add_f32_e32 v241, v109, v241
	v_add_f32_e32 v241, v110, v241
	v_add_f32_e32 v241, v111, v241
	v_fma_f32 v230, v230, v239, v241
	v_mul_f32_e32 v32, v239, v32
	v_mul_f32_e32 v33, v239, v33
	v_mul_f32_e32 v34, v239, v34
	v_mul_f32_e32 v35, v239, v35
	v_mul_f32_e32 v36, v239, v36
	v_mul_f32_e32 v37, v239, v37
	v_mul_f32_e32 v38, v239, v38
	v_mul_f32_e32 v39, v239, v39
	v_mul_f32_e32 v40, v239, v40
	v_mul_f32_e32 v41, v239, v41
	v_mul_f32_e32 v42, v239, v42
	v_mul_f32_e32 v43, v239, v43
	v_mul_f32_e32 v44, v239, v44
	v_mul_f32_e32 v45, v239, v45
	v_mul_f32_e32 v46, v239, v46
	v_mul_f32_e32 v47, v239, v47
	v_mul_f32_e32 v48, v239, v48
	v_mul_f32_e32 v49, v239, v49
	v_mul_f32_e32 v50, v239, v50
	v_mul_f32_e32 v51, v239, v51
	v_mul_f32_e32 v52, v239, v52
	v_mul_f32_e32 v53, v239, v53
	v_mul_f32_e32 v54, v239, v54
	v_mul_f32_e32 v55, v239, v55
	v_mul_f32_e32 v56, v239, v56
	v_mul_f32_e32 v57, v239, v57
	v_mul_f32_e32 v58, v239, v58
	v_mul_f32_e32 v59, v239, v59
	v_mul_f32_e32 v60, v239, v60
	v_mul_f32_e32 v61, v239, v61
	v_mul_f32_e32 v62, v239, v62
	v_mul_f32_e32 v63, v239, v63
	v_mul_f32_e32 v64, v239, v64
	v_mul_f32_e32 v65, v239, v65
	v_mul_f32_e32 v66, v239, v66
	v_mul_f32_e32 v67, v239, v67
	v_mul_f32_e32 v68, v239, v68
	v_mul_f32_e32 v69, v239, v69
	v_mul_f32_e32 v70, v239, v70
	v_mul_f32_e32 v71, v239, v71
	v_mul_f32_e32 v72, v239, v72
	v_mul_f32_e32 v73, v239, v73
	v_mul_f32_e32 v74, v239, v74
	v_mul_f32_e32 v75, v239, v75
	v_mul_f32_e32 v76, v239, v76
	v_mul_f32_e32 v77, v239, v77
	v_mul_f32_e32 v78, v239, v78
	v_mul_f32_e32 v79, v239, v79
	v_mul_f32_e32 v80, v239, v80
	v_mul_f32_e32 v81, v239, v81
	v_mul_f32_e32 v82, v239, v82
	v_mul_f32_e32 v83, v239, v83
	v_mul_f32_e32 v84, v239, v84
	v_mul_f32_e32 v85, v239, v85
	v_mul_f32_e32 v86, v239, v86
	v_mul_f32_e32 v87, v239, v87
	v_mul_f32_e32 v88, v239, v88
	v_mul_f32_e32 v89, v239, v89
	v_mul_f32_e32 v90, v239, v90
	v_mul_f32_e32 v91, v239, v91
	v_mul_f32_e32 v92, v239, v92
	v_mul_f32_e32 v93, v239, v93
	v_mul_f32_e32 v94, v239, v94
	v_mul_f32_e32 v95, v239, v95
	v_cvt_pk_bf16_f32 v212, v96, v97
	v_cvt_pk_bf16_f32 v213, v98, v99
	v_cvt_pk_bf16_f32 v214, v100, v101
	v_cvt_pk_bf16_f32 v215, v102, v103
	v_cvt_pk_bf16_f32 v216, v104, v105
	v_cvt_pk_bf16_f32 v217, v106, v107
	v_cvt_pk_bf16_f32 v218, v108, v109
	v_cvt_pk_bf16_f32 v219, v110, v111
	s_waitcnt vmcnt(0)
	ds_write_b128 v224, v[176:179]
	ds_write_b128 v224, v[180:183] offset:4608
	ds_write_b128 v224, v[184:187] offset:9216
	ds_write_b128 v224, v[188:191] offset:13824
	ds_write_b128 v224, v[192:195] offset:18432
	ds_write_b128 v224, v[196:199] offset:23040
	ds_write_b128 v224, v[200:203] offset:27648
	ds_write_b128 v224, v[204:207] offset:32256
	s_waitcnt lgkmcnt(0)
	s_barrier
	ds_read_b64 v[112:113], v226 offset:0
	ds_read_b64 v[114:115], v226 offset:32
	ds_read_b64 v[116:117], v226 offset:64
	ds_read_b64 v[118:119], v226 offset:96
	ds_read_b64 v[120:121], v226 offset:2304
	ds_read_b64 v[122:123], v226 offset:2336
	ds_read_b64 v[124:125], v226 offset:2368
	ds_read_b64 v[126:127], v226 offset:2400
	ds_read_b64 v[128:129], v226 offset:4608
	ds_read_b64 v[130:131], v226 offset:4640
	ds_read_b64 v[132:133], v226 offset:4672
	ds_read_b64 v[134:135], v226 offset:4704
	ds_read_b64 v[136:137], v226 offset:6912
	ds_read_b64 v[138:139], v226 offset:6944
	ds_read_b64 v[140:141], v226 offset:6976
	ds_read_b64 v[142:143], v226 offset:7008
	s_waitcnt lgkmcnt(14)
	v_mfma_f32_16x16x32_bf16 v[32:35], v[112:115], v[212:215], v[32:35]
	ds_read_b64 v[112:113], v226 offset:9216
	ds_read_b64 v[114:115], v226 offset:9248
	s_waitcnt lgkmcnt(14)
	v_mfma_f32_16x16x32_bf16 v[32:35], v[116:119], v[216:219], v[32:35]
	ds_read_b64 v[116:117], v226 offset:9280
	ds_read_b64 v[118:119], v226 offset:9312
	s_waitcnt lgkmcnt(14)
	v_mfma_f32_16x16x32_bf16 v[36:39], v[120:123], v[212:215], v[36:39]
	ds_read_b64 v[120:121], v226 offset:11520
	ds_read_b64 v[122:123], v226 offset:11552
	s_waitcnt lgkmcnt(14)
	v_mfma_f32_16x16x32_bf16 v[36:39], v[124:127], v[216:219], v[36:39]
	ds_read_b64 v[124:125], v226 offset:11584
	ds_read_b64 v[126:127], v226 offset:11616
	s_waitcnt lgkmcnt(14)
	v_mfma_f32_16x16x32_bf16 v[40:43], v[128:131], v[212:215], v[40:43]
	ds_read_b64 v[128:129], v226 offset:13824
	ds_read_b64 v[130:131], v226 offset:13856
	s_waitcnt lgkmcnt(14)
	v_mfma_f32_16x16x32_bf16 v[40:43], v[132:135], v[216:219], v[40:43]
	ds_read_b64 v[132:133], v226 offset:13888
	ds_read_b64 v[134:135], v226 offset:13920
	s_waitcnt lgkmcnt(14)
	v_mfma_f32_16x16x32_bf16 v[44:47], v[136:139], v[212:215], v[44:47]
	ds_read_b64 v[136:137], v226 offset:16128
	ds_read_b64 v[138:139], v226 offset:16160
	s_waitcnt lgkmcnt(14)
	v_mfma_f32_16x16x32_bf16 v[44:47], v[140:143], v[216:219], v[44:47]
	ds_read_b64 v[140:141], v226 offset:16192
	ds_read_b64 v[142:143], v226 offset:16224
	s_waitcnt lgkmcnt(14)
	v_mfma_f32_16x16x32_bf16 v[48:51], v[112:115], v[212:215], v[48:51]
	ds_read_b64 v[112:113], v226 offset:18432
	ds_read_b64 v[114:115], v226 offset:18464
	s_waitcnt lgkmcnt(14)
	v_mfma_f32_16x16x32_bf16 v[48:51], v[116:119], v[216:219], v[48:51]
	ds_read_b64 v[116:117], v226 offset:18496
	ds_read_b64 v[118:119], v226 offset:18528
	s_waitcnt lgkmcnt(14)
	v_mfma_f32_16x16x32_bf16 v[52:55], v[120:123], v[212:215], v[52:55]
	ds_read_b64 v[120:121], v226 offset:20736
	ds_read_b64 v[122:123], v226 offset:20768
	s_waitcnt lgkmcnt(14)
	v_mfma_f32_16x16x32_bf16 v[52:55], v[124:127], v[216:219], v[52:55]
	ds_read_b64 v[124:125], v226 offset:20800
	ds_read_b64 v[126:127], v226 offset:20832
	s_waitcnt lgkmcnt(14)
; DEVI f32x4 mfma16(bf16x8 a, bf16x8 b, f32x4 c) { return __builtin_amdgcn_mfma_f32_16x16x32_bf16(a, b, c, 0, 0, 0); }
; template <int DH, int NQ, int LDV>
; DEVI void attn_pv(const u16* sVt, const bf16x8 (&pb)[NQ][2], f32x4 (&o)[NQ][DH / 16], int lane) {
;   const int col = lane & 15, quad = lane >> 4;
;   __builtin_amdgcn_s_setprio(1);
; #pragma unroll
;   for (int dt = 0; dt < DH / 16; ++dt) {
; #pragma unroll
;     for (int kk = 0; kk < 2; ++kk) {
;       union { bf16x8 v; uint2 h[2]; } cv;
;       cv.h[0] = *(const uint2*)(sVt + (16 * dt + col) * LDV + 32 * kk + 4 * quad);
;       cv.h[1] = *(const uint2*)(sVt + (16 * dt + col) * LDV + 32 * kk + 16 + 4 * quad);
; #pragma unroll
;       for (int qt = 0; qt < NQ; ++qt) o[qt][dt] = mfma16(cv.v, pb[qt][kk], o[qt][dt]);
;     }
;   }
;   __builtin_amdgcn_s_setprio(0);
; }
; DEVI void phase_memattn(const Params& p, unsigned char* smem) {
;     ...
;     float lt = l[0];
;     lt += __shfl_xor(lt, 16);
;     lt += __shfl_xor(lt, 32);
	v_mfma_f32_16x16x32_bf16 v[56:59], v[128:131], v[212:215], v[56:59]
	ds_read_b64 v[128:129], v226 offset:23040
	ds_read_b64 v[130:131], v226 offset:23072
	s_waitcnt lgkmcnt(14)
	v_mfma_f32_16x16x32_bf16 v[56:59], v[132:135], v[216:219], v[56:59]
	ds_read_b64 v[132:133], v226 offset:23104
	ds_read_b64 v[134:135], v226 offset:23136
	s_waitcnt lgkmcnt(14)
	v_mfma_f32_16x16x32_bf16 v[60:63], v[136:139], v[212:215], v[60:63]
	ds_read_b64 v[136:137], v226 offset:25344
	ds_read_b64 v[138:139], v226 offset:25376
	s_waitcnt lgkmcnt(14)
	v_mfma_f32_16x16x32_bf16 v[60:63], v[140:143], v[216:219], v[60:63]
	ds_read_b64 v[140:141], v226 offset:25408
	ds_read_b64 v[142:143], v226 offset:25440
	s_waitcnt lgkmcnt(14)
	v_mfma_f32_16x16x32_bf16 v[64:67], v[112:115], v[212:215], v[64:67]
	ds_read_b64 v[112:113], v226 offset:27648
	ds_read_b64 v[114:115], v226 offset:27680
	s_waitcnt lgkmcnt(14)
	v_mfma_f32_16x16x32_bf16 v[64:67], v[116:119], v[216:219], v[64:67]
	ds_read_b64 v[116:117], v226 offset:27712
	ds_read_b64 v[118:119], v226 offset:27744
	s_waitcnt lgkmcnt(14)
	v_mfma_f32_16x16x32_bf16 v[68:71], v[120:123], v[212:215], v[68:71]
	ds_read_b64 v[120:121], v226 offset:29952
	ds_read_b64 v[122:123], v226 offset:29984
	s_waitcnt lgkmcnt(14)
	v_mfma_f32_16x16x32_bf16 v[68:71], v[124:127], v[216:219], v[68:71]
	ds_read_b64 v[124:125], v226 offset:30016
	ds_read_b64 v[126:127], v226 offset:30048
	s_waitcnt lgkmcnt(14)
	v_mfma_f32_16x16x32_bf16 v[72:75], v[128:131], v[212:215], v[72:75]
	ds_read_b64 v[128:129], v226 offset:32256
	ds_read_b64 v[130:131], v226 offset:32288
	s_waitcnt lgkmcnt(14)
	v_mfma_f32_16x16x32_bf16 v[72:75], v[132:135], v[216:219], v[72:75]
	ds_read_b64 v[132:133], v226 offset:32320
	ds_read_b64 v[134:135], v226 offset:32352
	s_waitcnt lgkmcnt(14)
	v_mfma_f32_16x16x32_bf16 v[76:79], v[136:139], v[212:215], v[76:79]
	ds_read_b64 v[136:137], v226 offset:34560
	ds_read_b64 v[138:139], v226 offset:34592
	s_waitcnt lgkmcnt(14)
	v_mfma_f32_16x16x32_bf16 v[76:79], v[140:143], v[216:219], v[76:79]
	ds_read_b64 v[140:141], v226 offset:34624
	ds_read_b64 v[142:143], v226 offset:34656
	s_waitcnt lgkmcnt(14)
	v_mfma_f32_16x16x32_bf16 v[80:83], v[112:115], v[212:215], v[80:83]
	s_waitcnt lgkmcnt(12)
	v_mfma_f32_16x16x32_bf16 v[80:83], v[116:119], v[216:219], v[80:83]
	s_waitcnt lgkmcnt(10)
	v_mfma_f32_16x16x32_bf16 v[84:87], v[120:123], v[212:215], v[84:87]
	s_waitcnt lgkmcnt(8)
	v_mfma_f32_16x16x32_bf16 v[84:87], v[124:127], v[216:219], v[84:87]
	s_waitcnt lgkmcnt(6)
	v_mfma_f32_16x16x32_bf16 v[88:91], v[128:131], v[212:215], v[88:91]
	s_waitcnt lgkmcnt(4)
	v_mfma_f32_16x16x32_bf16 v[88:91], v[132:135], v[216:219], v[88:91]
	s_waitcnt lgkmcnt(2)
	v_mfma_f32_16x16x32_bf16 v[92:95], v[136:139], v[212:215], v[92:95]
	s_waitcnt lgkmcnt(0)
	v_mfma_f32_16x16x32_bf16 v[92:95], v[140:143], v[216:219], v[92:95]
	s_nop 7
	v_mov_b32_e32 v235, v230
	ds_bpermute_b32 v236, v228, v235
	s_waitcnt lgkmcnt(0)
; DEVI unsigned pack2(float a, float b) { return (unsigned)f2bf(a) | ((unsigned)f2bf(b) << 16); }
; DEVI void phase_memattn(const Params& p, unsigned char* smem) {
;     ...
;     float lt = l[0];
;     lt += __shfl_xor(lt, 16);
;     lt += __shfl_xor(lt, 32);
;     const float inv = 1.f / lt;
; #pragma unroll
;     for (int dt = 0; dt < 16; ++dt) {
;       uint2 pk;
;       pk.x = pack2(o[0][dt][0] * inv, o[0][dt][1] * inv);
;       pk.y = pack2(o[0][dt][2] * inv, o[0][dt][3] * inv);
;       *(uint2*)(p.mix + tok * LDA + head * 256 + 16 * dt + 4 * quad) = pk;
;     }
	v_add_f32_e32 v235, v236, v235
	v_mov_b32_e32 v236, v235
	v_mov_b32_e32 v237, v235
	s_nop 1
	v_permlane32_swap_b32_e32 v236, v237
	v_add_f32_e32 v235, v236, v237
	v_rcp_f32_e32 v238, v235
	s_nop 0
	v_fma_f32 v239, -v235, v238, 1.0
	v_fma_f32 v238, v239, v238, v238
	v_and_b32_e32 v96, 63, v210
	v_lshrrev_b32_e32 v99, 6, v210
	v_and_b32_e32 v100, 15, v96
	v_lshrrev_b32_e32 v101, 4, v96
	v_lshlrev_b32_e32 v102, 13, v99
	v_lshl_add_u32 v102, v100, 9, v102
	v_and_b32_e32 v97, 1, v101
	v_lshl_add_u32 v102, v97, 3, v102
	v_lshrrev_b32_e32 v101, 1, v101
	v_and_b32_e32 v100, 7, v100
	v_xor_b32_e32 v101, v100, v101
	v_xor_b32_e32 v98, 0, v101
	v_lshl_add_u32 v112, v98, 4, v102
	v_xor_b32_e32 v98, 2, v101
	v_lshl_add_u32 v113, v98, 4, v102
	v_xor_b32_e32 v98, 4, v101
	v_lshl_add_u32 v114, v98, 4, v102
	v_xor_b32_e32 v98, 6, v101
	v_lshl_add_u32 v115, v98, 4, v102
	v_mul_f32_e32 v32, v238, v32
	v_mul_f32_e32 v33, v238, v33
	v_mul_f32_e32 v34, v238, v34
	v_mul_f32_e32 v35, v238, v35
	v_cvt_pk_bf16_f32 v212, v32, v33
	v_cvt_pk_bf16_f32 v213, v34, v35
	ds_write_b64 v112, v[212:213]
	v_mul_f32_e32 v36, v238, v36
	v_mul_f32_e32 v37, v238, v37
	v_mul_f32_e32 v38, v238, v38
	v_mul_f32_e32 v39, v238, v39
	v_cvt_pk_bf16_f32 v214, v36, v37
	v_cvt_pk_bf16_f32 v215, v38, v39
	ds_write_b64 v113, v[214:215]
	v_mul_f32_e32 v40, v238, v40
	v_mul_f32_e32 v41, v238, v41
	v_mul_f32_e32 v42, v238, v42
	v_mul_f32_e32 v43, v238, v43
	v_cvt_pk_bf16_f32 v212, v40, v41
	v_cvt_pk_bf16_f32 v213, v42, v43
	ds_write_b64 v114, v[212:213]
	v_mul_f32_e32 v44, v238, v44
	v_mul_f32_e32 v45, v238, v45
	v_mul_f32_e32 v46, v238, v46
	v_mul_f32_e32 v47, v238, v47
	v_cvt_pk_bf16_f32 v214, v44, v45
	v_cvt_pk_bf16_f32 v215, v46, v47
	ds_write_b64 v115, v[214:215]
	v_mul_f32_e32 v48, v238, v48
	v_mul_f32_e32 v49, v238, v49
	v_mul_f32_e32 v50, v238, v50
	v_mul_f32_e32 v51, v238, v51
	v_cvt_pk_bf16_f32 v212, v48, v49
	v_cvt_pk_bf16_f32 v213, v50, v51
	ds_write_b64 v112, v[212:213] offset:128
	v_mul_f32_e32 v52, v238, v52
	v_mul_f32_e32 v53, v238, v53
	v_mul_f32_e32 v54, v238, v54
	v_mul_f32_e32 v55, v238, v55
	v_cvt_pk_bf16_f32 v214, v52, v53
	v_cvt_pk_bf16_f32 v215, v54, v55
	ds_write_b64 v113, v[214:215] offset:128
	v_mul_f32_e32 v56, v238, v56
	v_mul_f32_e32 v57, v238, v57
	v_mul_f32_e32 v58, v238, v58
	v_mul_f32_e32 v59, v238, v59
	v_cvt_pk_bf16_f32 v212, v56, v57
	v_cvt_pk_bf16_f32 v213, v58, v59
	ds_write_b64 v114, v[212:213] offset:128
	v_mul_f32_e32 v60, v238, v60
	v_mul_f32_e32 v61, v238, v61
	v_mul_f32_e32 v62, v238, v62
	v_mul_f32_e32 v63, v238, v63
	v_cvt_pk_bf16_f32 v214, v60, v61
	v_cvt_pk_bf16_f32 v215, v62, v63
	ds_write_b64 v115, v[214:215] offset:128
	v_mul_f32_e32 v64, v238, v64
	v_mul_f32_e32 v65, v238, v65
	v_mul_f32_e32 v66, v238, v66
	v_mul_f32_e32 v67, v238, v67
	v_cvt_pk_bf16_f32 v212, v64, v65
	v_cvt_pk_bf16_f32 v213, v66, v67
	ds_write_b64 v112, v[212:213] offset:256
	v_mul_f32_e32 v68, v238, v68
	v_mul_f32_e32 v69, v238, v69
	v_mul_f32_e32 v70, v238, v70
	v_mul_f32_e32 v71, v238, v71
	v_cvt_pk_bf16_f32 v214, v68, v69
	v_cvt_pk_bf16_f32 v215, v70, v71
	ds_write_b64 v113, v[214:215] offset:256
	v_mul_f32_e32 v72, v238, v72
	v_mul_f32_e32 v73, v238, v73
	v_mul_f32_e32 v74, v238, v74
	v_mul_f32_e32 v75, v238, v75
	v_cvt_pk_bf16_f32 v212, v72, v73
	v_cvt_pk_bf16_f32 v213, v74, v75
	ds_write_b64 v114, v[212:213] offset:256
	v_mul_f32_e32 v76, v238, v76
	v_mul_f32_e32 v77, v238, v77
	v_mul_f32_e32 v78, v238, v78
	v_mul_f32_e32 v79, v238, v79
	v_cvt_pk_bf16_f32 v214, v76, v77
	v_cvt_pk_bf16_f32 v215, v78, v79
	ds_write_b64 v115, v[214:215] offset:256
	v_mul_f32_e32 v80, v238, v80
	v_mul_f32_e32 v81, v238, v81
	v_mul_f32_e32 v82, v238, v82
	v_mul_f32_e32 v83, v238, v83
	v_cvt_pk_bf16_f32 v212, v80, v81
	v_cvt_pk_bf16_f32 v213, v82, v83
	ds_write_b64 v112, v[212:213] offset:384
	v_mul_f32_e32 v84, v238, v84
	v_mul_f32_e32 v85, v238, v85
	v_mul_f32_e32 v86, v238, v86
	v_mul_f32_e32 v87, v238, v87
	v_cvt_pk_bf16_f32 v214, v84, v85
	v_cvt_pk_bf16_f32 v215, v86, v87
	ds_write_b64 v113, v[214:215] offset:384
	v_mul_f32_e32 v88, v238, v88
	v_mul_f32_e32 v89, v238, v89
	v_mul_f32_e32 v90, v238, v90
	v_mul_f32_e32 v91, v238, v91
	v_cvt_pk_bf16_f32 v212, v88, v89
	v_cvt_pk_bf16_f32 v213, v90, v91
	ds_write_b64 v114, v[212:213] offset:384
	v_mul_f32_e32 v92, v238, v92
	v_mul_f32_e32 v93, v238, v93
	v_mul_f32_e32 v94, v238, v94
	v_mul_f32_e32 v95, v238, v95
	v_cvt_pk_bf16_f32 v214, v92, v93
	v_cvt_pk_bf16_f32 v215, v94, v95
	ds_write_b64 v115, v[214:215] offset:384
	v_lshrrev_b32_e32 v97, 5, v96
	v_and_b32_e32 v98, 31, v96
	v_lshlrev_b32_e32 v116, 13, v99
	v_lshl_add_u32 v116, v97, 9, v116
	v_lshl_add_u32 v116, v98, 4, v116
	v_mul_u32_u24_e32 v117, 0x8800, v99
	v_mul_u32_u24_e32 v102, 0x880, v97
	v_add_u32_e32 v117, v102, v117
	v_add_u32_e32 v117, s13, v117
	v_xor_b32_e32 v98, v97, v98
	v_xor_b32_e32 v102, 0, v98
	v_lshl_add_u32 v118, v102, 4, v117
	v_xor_b32_e32 v102, 2, v98
	v_lshl_add_u32 v119, v102, 4, v117
	v_xor_b32_e32 v102, 4, v98
	v_lshl_add_u32 v120, v102, 4, v117
	v_xor_b32_e32 v102, 6, v98
	v_lshl_add_u32 v121, v102, 4, v117
	s_waitcnt lgkmcnt(0)
	ds_read_b128 v[144:147], v116
	ds_read_b128 v[148:151], v116 offset:1024
	ds_read_b128 v[152:155], v116 offset:2048
	ds_read_b128 v[156:159], v116 offset:3072
	ds_read_b128 v[160:163], v116 offset:4096
	ds_read_b128 v[164:167], v116 offset:5120
	ds_read_b128 v[168:171], v116 offset:6144
	ds_read_b128 v[172:175], v116 offset:7168
	s_waitcnt lgkmcnt(7)
	global_store_dwordx4 v118, v[144:147], s[6:7]
	s_waitcnt lgkmcnt(6)
	v_add_u32_e32 v102, 0x1100, v119
	global_store_dwordx4 v102, v[148:151], s[6:7]
	s_waitcnt lgkmcnt(5)
	v_add_u32_e32 v102, 0x2200, v120
	global_store_dwordx4 v102, v[152:155], s[6:7]
	s_waitcnt lgkmcnt(4)
	v_add_u32_e32 v102, 0x3300, v121
	global_store_dwordx4 v102, v[156:159], s[6:7]
	s_waitcnt lgkmcnt(3)
	v_add_u32_e32 v102, 0x4400, v118
	global_store_dwordx4 v102, v[160:163], s[6:7]
	s_waitcnt lgkmcnt(2)
	v_add_u32_e32 v102, 0x5500, v119
	global_store_dwordx4 v102, v[164:167], s[6:7]
	s_waitcnt lgkmcnt(1)
	v_add_u32_e32 v102, 0x6600, v120
	global_store_dwordx4 v102, v[168:171], s[6:7]
	s_waitcnt lgkmcnt(0)
	v_add_u32_e32 v102, 0x7700, v121
	global_store_dwordx4 v102, v[172:175], s[6:7]
	s_barrier
	s_add_u32 s8, s8, s9
	s_cmp_lt_u32 s8, 0x800
	s_cbranch_scc1 .Lp7_tile
